# v55 + nt on the residual-stream loads/stores of the EpiRes epilogues
# speedup vs baseline: 1.1474x; 1.1474x over previous
.LBB0_514:
	v_mov_b32_e32 v70, v0
	s_lshl_b32 s0, s40, 8
	s_add_i32 s0, s0, s54
	v_bfe_u32 v239, v70, 4, 2
	v_and_or_b32 v228, v70, 15, s0
	s_or_b32 s0, s64, s67
	v_lshlrev_b32_e32 v70, 3, v239
	v_or_b32_e32 v214, s0, v70
	v_or_b32_e32 v70, s67, v70
	v_ashrrev_i32_e32 v215, 31, v214
	v_ashrrev_i32_e32 v229, 31, v228
	v_lshlrev_b32_e32 v238, 2, v70
	v_lshl_add_u64 v[70:71], v[214:215], 1, s[10:11]
	v_lshlrev_b64 v[72:73], 12, v[228:229]
	v_lshl_add_u64 v[72:73], v[70:71], 0, v[72:73]
	global_load_dwordx4 v[190:193], v[72:73], off nt
	global_load_dwordx4 v[186:189], v[72:73], off offset:256 nt
	v_or_b32_e32 v230, 16, v228
	v_ashrrev_i32_e32 v231, 31, v230
	v_lshlrev_b64 v[72:73], 12, v[230:231]
	v_or_b32_e32 v226, 32, v228
	v_lshl_add_u64 v[72:73], v[70:71], 0, v[72:73]
	v_ashrrev_i32_e32 v227, 31, v226
	global_load_dwordx4 v[182:185], v[72:73], off nt
	global_load_dwordx4 v[178:181], v[72:73], off offset:256 nt
	v_lshlrev_b64 v[72:73], 12, v[226:227]
	v_or_b32_e32 v224, 48, v228
	v_lshl_add_u64 v[72:73], v[70:71], 0, v[72:73]
	v_ashrrev_i32_e32 v225, 31, v224
	global_load_dwordx4 v[166:169], v[72:73], off nt
	global_load_dwordx4 v[162:165], v[72:73], off offset:256 nt
	v_lshlrev_b64 v[72:73], 12, v[224:225]
	v_add_u32_e32 v222, 0x80, v228
	v_lshl_add_u64 v[72:73], v[70:71], 0, v[72:73]
	v_ashrrev_i32_e32 v223, 31, v222
	global_load_dwordx4 v[158:161], v[72:73], off nt
	global_load_dwordx4 v[154:157], v[72:73], off offset:256 nt
	v_lshlrev_b64 v[72:73], 12, v[222:223]
	v_add_u32_e32 v220, 0x90, v228
	v_lshl_add_u64 v[72:73], v[70:71], 0, v[72:73]
	v_ashrrev_i32_e32 v221, 31, v220
	global_load_dwordx4 v[142:145], v[72:73], off nt
	global_load_dwordx4 v[134:137], v[72:73], off offset:256 nt
	v_lshlrev_b64 v[72:73], 12, v[220:221]
	v_add_u32_e32 v218, 0xa0, v228
	v_lshl_add_u64 v[72:73], v[70:71], 0, v[72:73]
	v_ashrrev_i32_e32 v219, 31, v218
	global_load_dwordx4 v[126:129], v[72:73], off nt
	global_load_dwordx4 v[114:117], v[72:73], off offset:256 nt
	v_lshlrev_b64 v[72:73], 12, v[218:219]
	v_add_u32_e32 v216, 0xb0, v228
	v_lshl_add_u64 v[72:73], v[70:71], 0, v[72:73]
	v_ashrrev_i32_e32 v217, 31, v216
	global_load_dwordx4 v[102:105], v[72:73], off nt
	global_load_dwordx4 v[90:93], v[72:73], off offset:256 nt
	v_lshlrev_b64 v[72:73], 12, v[216:217]
	v_lshl_add_u64 v[70:71], v[70:71], 0, v[72:73]
	global_load_dwordx4 v[78:81], v[70:71], off nt
	s_nop 0
	global_load_dwordx4 v[70:73], v[70:71], off offset:256 nt
	v_add_u32_e32 v238, 0, v238
	v_add_u32_e32 v238, 0x24400, v238
	v_lshlrev_b64 v[240:241], 11, v[228:229]
	v_lshl_add_u64 v[248:249], v[240:241], 0, v[214:215]
	ds_read_b128 v[240:243], v238
	ds_read_b128 v[244:247], v238 offset:16
	v_cmp_eq_u32_e32 vcc, 0, v239
	s_waitcnt vmcnt(0)
	v_lshlrev_b32_e32 v250, 16, v190
	v_and_b32_e32 v251, 0xffff0000, v190
	v_lshlrev_b32_e32 v190, 16, v191
	v_and_b32_e32 v191, 0xffff0000, v191
	s_waitcnt lgkmcnt(1)
	v_pk_fma_f32 v[176:177], v[176:177], v[242:243], v[190:191]
	v_lshlrev_b32_e32 v190, 16, v192
	v_and_b32_e32 v191, 0xffff0000, v192
	v_lshlrev_b32_e32 v192, 16, v193
	v_and_b32_e32 v193, 0xffff0000, v193
	s_waitcnt lgkmcnt(0)
	v_pk_fma_f32 v[192:193], v[172:173], v[246:247], v[192:193]
	v_pk_fma_f32 v[172:173], v[170:171], v[244:245], v[190:191]
	v_lshlrev_b64 v[190:191], 1, v[248:249]
	v_pk_fma_f32 v[174:175], v[174:175], v[240:241], v[250:251]
	s_nop 0
	v_cvt_pk_bf16_f32 v170, v174, v175
	v_cvt_pk_bf16_f32 v171, v176, v177
	v_cvt_pk_bf16_f32 v172, v172, v173
	v_cvt_pk_bf16_f32 v173, v192, v193
	v_lshl_add_u64 v[192:193], s[12:13], 0, v[190:191]
	v_and_b32_e32 v241, 0xffff0000, v170
	v_and_b32_e32 v243, 0xffff0000, v171
	global_store_dwordx4 v[192:193], v[170:173], off nt
	v_lshlrev_b32_e32 v240, 16, v170
	v_lshlrev_b32_e32 v242, 16, v171
	v_mul_f32_e32 v170, v241, v241
	v_mul_f32_e32 v171, v243, v243
	v_and_b32_e32 v245, 0xffff0000, v172
	v_and_b32_e32 v247, 0xffff0000, v173
	v_fmac_f32_e32 v170, v240, v240
	v_fmac_f32_e32 v171, v242, v242
	v_lshlrev_b32_e32 v244, 16, v172
	v_lshlrev_b32_e32 v246, 16, v173
	v_add_f32_e32 v170, v170, v171
	v_mul_f32_e32 v171, v245, v245
	v_mul_f32_e32 v172, v247, v247
	v_fmac_f32_e32 v171, v244, v244
	v_fmac_f32_e32 v172, v246, v246
	v_add_f32_e32 v171, v171, v172
	v_add_f32_e32 v239, v170, v171
	ds_read_b128 v[170:173], v238 offset:1024
	ds_read_b128 v[174:177], v238 offset:1040
	v_lshl_add_u64 v[190:191], s[36:37], 0, v[190:191]
	s_waitcnt lgkmcnt(1)
	v_pk_mul_f32 v[172:173], v[172:173], v[242:243]
	v_pk_mul_f32 v[170:171], v[170:171], v[240:241]
	s_waitcnt lgkmcnt(0)
	v_pk_mul_f32 v[176:177], v[176:177], v[246:247]
	v_pk_mul_f32 v[174:175], v[174:175], v[244:245]
	v_cvt_pk_bf16_f32 v170, v170, v171
	v_cvt_pk_bf16_f32 v171, v172, v173
	v_lshlrev_b32_e32 v240, 16, v186
	v_cvt_pk_bf16_f32 v172, v174, v175
	v_cvt_pk_bf16_f32 v173, v176, v177
	global_store_dwordx4 v[190:191], v[170:173], off nt
	ds_read_b128 v[170:173], v238 offset:512
	ds_read_b128 v[174:177], v238 offset:528
	v_and_b32_e32 v241, 0xffff0000, v186
	v_lshlrev_b32_e32 v186, 16, v187
	v_and_b32_e32 v187, 0xffff0000, v187
	s_waitcnt lgkmcnt(1)
	v_pk_fma_f32 v[152:153], v[152:153], v[172:173], v[186:187]
	v_pk_fma_f32 v[150:151], v[150:151], v[170:171], v[240:241]
	v_lshlrev_b32_e32 v170, 16, v188
	v_and_b32_e32 v171, 0xffff0000, v188
	v_lshlrev_b32_e32 v172, 16, v189
	v_and_b32_e32 v173, 0xffff0000, v189
	s_waitcnt lgkmcnt(0)
	v_pk_fma_f32 v[172:173], v[148:149], v[176:177], v[172:173]
	v_pk_fma_f32 v[148:149], v[146:147], v[174:175], v[170:171]
	v_cvt_pk_bf16_f32 v146, v150, v151
	v_cvt_pk_bf16_f32 v147, v152, v153
	s_nop 0
	v_cvt_pk_bf16_f32 v148, v148, v149
	v_cvt_pk_bf16_f32 v149, v172, v173
	v_and_b32_e32 v171, 0xffff0000, v146
	v_and_b32_e32 v173, 0xffff0000, v147
	global_store_dwordx4 v[192:193], v[146:149], off offset:256 nt
	v_lshlrev_b32_e32 v170, 16, v146
	v_lshlrev_b32_e32 v172, 16, v147
	v_mul_f32_e32 v146, v171, v171
	v_mul_f32_e32 v147, v173, v173
	v_and_b32_e32 v175, 0xffff0000, v148
	v_and_b32_e32 v177, 0xffff0000, v149
	v_fmac_f32_e32 v146, v170, v170
	v_fmac_f32_e32 v147, v172, v172
	v_lshlrev_b32_e32 v174, 16, v148
	v_lshlrev_b32_e32 v176, 16, v149
	v_add_f32_e32 v146, v146, v147
	v_mul_f32_e32 v147, v175, v175
	v_mul_f32_e32 v148, v177, v177
	v_fmac_f32_e32 v147, v174, v174
	v_fmac_f32_e32 v148, v176, v176
	v_add_f32_e32 v147, v147, v148
	v_add_f32_e32 v146, v146, v147
	v_add_f32_e32 v186, v239, v146
	ds_read_b128 v[146:149], v238 offset:1536
	ds_read_b128 v[150:153], v238 offset:1552
	s_waitcnt lgkmcnt(1)
	v_pk_mul_f32 v[146:147], v[146:147], v[170:171]
	v_pk_mul_f32 v[148:149], v[148:149], v[172:173]
	v_cvt_pk_bf16_f32 v146, v146, v147
	s_waitcnt lgkmcnt(0)
	v_pk_mul_f32 v[152:153], v[152:153], v[176:177]
	v_pk_mul_f32 v[150:151], v[150:151], v[174:175]
	v_cvt_pk_bf16_f32 v147, v148, v149
	s_nop 0
	v_cvt_pk_bf16_f32 v148, v150, v151
	v_cvt_pk_bf16_f32 v149, v152, v153
	global_store_dwordx4 v[190:191], v[146:149], off offset:256 nt
	ds_swizzle_b32 v146, v186 offset:swizzle(SWAP,16)
	s_waitcnt lgkmcnt(0)
	v_add_f32_e32 v148, v186, v146
	v_mov_b32_e32 v149, v148
	s_nop 1
	v_permlane32_swap_b32_e32 v148, v149
	v_lshl_add_u64 v[146:147], v[228:229], 2, s[38:39]
	s_and_saveexec_b64 s[22:23], vcc
	s_cbranch_execz .LBB0_516
	v_add_f32_e32 v148, v148, v149
	v_fma_f32 v148, v148, s74, 0.5
	v_cvt_u32_f32_e32 v148, v148
	global_atomic_add v[146:147], v148, off
.LBB0_516:
	s_or_b64 exec, exec, s[22:23]
	v_lshlrev_b64 v[148:149], 11, v[230:231]
	v_lshl_add_u64 v[152:153], v[148:149], 0, v[214:215]
	ds_read_b128 v[148:151], v238
	ds_read_b128 v[170:173], v238 offset:16
	v_lshlrev_b32_e32 v174, 16, v182
	v_and_b32_e32 v175, 0xffff0000, v182
	v_lshlrev_b32_e32 v176, 16, v183
	v_and_b32_e32 v177, 0xffff0000, v183
	s_waitcnt lgkmcnt(1)
	v_pk_fma_f32 v[140:141], v[140:141], v[150:151], v[176:177]
	v_pk_fma_f32 v[138:139], v[138:139], v[148:149], v[174:175]
	v_lshlrev_b32_e32 v148, 16, v184
	v_and_b32_e32 v149, 0xffff0000, v184
	v_lshlrev_b32_e32 v150, 16, v185
	v_and_b32_e32 v151, 0xffff0000, v185
	s_waitcnt lgkmcnt(0)
	v_pk_fma_f32 v[150:151], v[132:133], v[172:173], v[150:151]
	v_pk_fma_f32 v[132:133], v[130:131], v[170:171], v[148:149]
	v_lshlrev_b64 v[148:149], 1, v[152:153]
	v_cvt_pk_bf16_f32 v130, v138, v139
	v_cvt_pk_bf16_f32 v131, v140, v141
	v_cvt_pk_bf16_f32 v132, v132, v133
	v_cvt_pk_bf16_f32 v133, v150, v151
	v_lshl_add_u64 v[150:151], s[12:13], 0, v[148:149]
	v_and_b32_e32 v153, 0xffff0000, v130
	v_and_b32_e32 v171, 0xffff0000, v131
	global_store_dwordx4 v[150:151], v[130:133], off nt
	v_lshlrev_b32_e32 v152, 16, v130
	v_lshlrev_b32_e32 v170, 16, v131
	v_and_b32_e32 v173, 0xffff0000, v132
	v_and_b32_e32 v175, 0xffff0000, v133
	v_mul_f32_e32 v130, v153, v153
	v_mul_f32_e32 v131, v171, v171
	v_lshlrev_b32_e32 v172, 16, v132
	v_lshlrev_b32_e32 v174, 16, v133
	v_fmac_f32_e32 v130, v152, v152
	v_fmac_f32_e32 v131, v170, v170
	v_mul_f32_e32 v138, v173, v173
	v_mul_f32_e32 v139, v175, v175
	v_add_f32_e32 v176, v130, v131
	v_fmac_f32_e32 v138, v172, v172
	v_fmac_f32_e32 v139, v174, v174
	ds_read_b128 v[130:133], v238 offset:1024
	v_add_f32_e32 v177, v138, v139
	ds_read_b128 v[138:141], v238 offset:1040
	v_lshl_add_u64 v[148:149], s[36:37], 0, v[148:149]
	v_add_f32_e32 v176, v176, v177
	s_waitcnt lgkmcnt(1)
	v_pk_mul_f32 v[132:133], v[132:133], v[170:171]
	v_pk_mul_f32 v[130:131], v[130:131], v[152:153]
	s_waitcnt lgkmcnt(0)
	v_pk_mul_f32 v[140:141], v[140:141], v[174:175]
	v_pk_mul_f32 v[138:139], v[138:139], v[172:173]
	v_cvt_pk_bf16_f32 v130, v130, v131
	v_cvt_pk_bf16_f32 v131, v132, v133
	v_lshlrev_b32_e32 v152, 16, v178
	v_cvt_pk_bf16_f32 v132, v138, v139
	v_cvt_pk_bf16_f32 v133, v140, v141
	global_store_dwordx4 v[148:149], v[130:133], off nt
	ds_read_b128 v[130:133], v238 offset:512
	ds_read_b128 v[138:141], v238 offset:528
	v_and_b32_e32 v153, 0xffff0000, v178
	v_lshlrev_b32_e32 v170, 16, v179
	v_and_b32_e32 v171, 0xffff0000, v179
	s_waitcnt lgkmcnt(1)
	v_pk_fma_f32 v[124:125], v[124:125], v[132:133], v[170:171]
	v_pk_fma_f32 v[122:123], v[122:123], v[130:131], v[152:153]
	v_lshlrev_b32_e32 v130, 16, v180
	v_and_b32_e32 v131, 0xffff0000, v180
	v_lshlrev_b32_e32 v132, 16, v181
	v_and_b32_e32 v133, 0xffff0000, v181
	s_waitcnt lgkmcnt(0)
	v_pk_fma_f32 v[132:133], v[120:121], v[140:141], v[132:133]
	v_pk_fma_f32 v[120:121], v[118:119], v[138:139], v[130:131]
	v_cvt_pk_bf16_f32 v118, v122, v123
	v_cvt_pk_bf16_f32 v119, v124, v125
	s_nop 0
	v_cvt_pk_bf16_f32 v120, v120, v121
	v_cvt_pk_bf16_f32 v121, v132, v133
	v_and_b32_e32 v131, 0xffff0000, v118
	v_and_b32_e32 v133, 0xffff0000, v119
	global_store_dwordx4 v[150:151], v[118:121], off offset:256 nt
	v_lshlrev_b32_e32 v130, 16, v118
	v_lshlrev_b32_e32 v132, 16, v119
	v_mul_f32_e32 v118, v131, v131
	v_mul_f32_e32 v119, v133, v133
	v_and_b32_e32 v139, 0xffff0000, v120
	v_and_b32_e32 v141, 0xffff0000, v121
	v_fmac_f32_e32 v118, v130, v130
	v_fmac_f32_e32 v119, v132, v132
	v_lshlrev_b32_e32 v138, 16, v120
	v_lshlrev_b32_e32 v140, 16, v121
	v_add_f32_e32 v150, v118, v119
	v_mul_f32_e32 v122, v139, v139
	v_mul_f32_e32 v123, v141, v141
	ds_read_b128 v[118:121], v238 offset:1536
	v_fmac_f32_e32 v122, v138, v138
	v_fmac_f32_e32 v123, v140, v140
	v_add_f32_e32 v151, v122, v123
	v_add_f32_e32 v150, v150, v151
	v_add_f32_e32 v150, v176, v150
	ds_read_b128 v[122:125], v238 offset:1552
	s_waitcnt lgkmcnt(1)
	v_pk_mul_f32 v[118:119], v[118:119], v[130:131]
	ds_swizzle_b32 v130, v150 offset:swizzle(SWAP,16)
	v_pk_mul_f32 v[120:121], v[120:121], v[132:133]
	v_cvt_pk_bf16_f32 v118, v118, v119
	s_waitcnt lgkmcnt(1)
	v_pk_mul_f32 v[124:125], v[124:125], v[140:141]
	v_pk_mul_f32 v[122:123], v[122:123], v[138:139]
	v_cvt_pk_bf16_f32 v119, v120, v121
	s_nop 0
	v_cvt_pk_bf16_f32 v120, v122, v123
	v_cvt_pk_bf16_f32 v121, v124, v125
	global_store_dwordx4 v[148:149], v[118:121], off offset:256 nt
	s_waitcnt lgkmcnt(0)
	s_nop 0
	v_add_f32_e32 v118, v150, v130
	v_mov_b32_e32 v119, v118
	s_nop 1
	v_permlane32_swap_b32_e32 v118, v119
	s_and_saveexec_b64 s[22:23], vcc
	s_cbranch_execz .LBB0_518
	v_add_f32_e32 v118, v118, v119
	v_fma_f32 v118, v118, s74, 0.5
	v_cvt_u32_f32_e32 v118, v118
	global_atomic_add v[146:147], v118, off offset:64
.LBB0_518:
	s_or_b64 exec, exec, s[22:23]
	v_lshlrev_b64 v[118:119], 11, v[226:227]
	v_lshl_add_u64 v[130:131], v[118:119], 0, v[214:215]
	ds_read_b128 v[118:121], v238
	ds_read_b128 v[122:125], v238 offset:16
	v_lshlrev_b32_e32 v132, 16, v166
	v_and_b32_e32 v133, 0xffff0000, v166
	v_lshlrev_b32_e32 v138, 16, v167
	v_and_b32_e32 v139, 0xffff0000, v167
	s_waitcnt lgkmcnt(1)
	v_pk_fma_f32 v[112:113], v[112:113], v[120:121], v[138:139]
	v_pk_fma_f32 v[110:111], v[110:111], v[118:119], v[132:133]
	v_lshlrev_b32_e32 v118, 16, v168
	v_and_b32_e32 v119, 0xffff0000, v168
	v_lshlrev_b32_e32 v120, 16, v169
	v_and_b32_e32 v121, 0xffff0000, v169
	s_waitcnt lgkmcnt(0)
	v_pk_fma_f32 v[120:121], v[108:109], v[124:125], v[120:121]
	v_pk_fma_f32 v[108:109], v[106:107], v[122:123], v[118:119]
	v_lshlrev_b64 v[118:119], 1, v[130:131]
	v_cvt_pk_bf16_f32 v106, v110, v111
	v_cvt_pk_bf16_f32 v107, v112, v113
	v_cvt_pk_bf16_f32 v108, v108, v109
	v_cvt_pk_bf16_f32 v109, v120, v121
	v_lshl_add_u64 v[120:121], s[12:13], 0, v[118:119]
	v_and_b32_e32 v123, 0xffff0000, v106
	v_and_b32_e32 v125, 0xffff0000, v107
	global_store_dwordx4 v[120:121], v[106:109], off nt
	v_lshlrev_b32_e32 v122, 16, v106
	v_lshlrev_b32_e32 v124, 16, v107
	v_and_b32_e32 v131, 0xffff0000, v108
	v_and_b32_e32 v133, 0xffff0000, v109
	v_mul_f32_e32 v106, v123, v123
	v_mul_f32_e32 v107, v125, v125
	v_lshlrev_b32_e32 v130, 16, v108
	v_lshlrev_b32_e32 v132, 16, v109
	v_fmac_f32_e32 v106, v122, v122
	v_fmac_f32_e32 v107, v124, v124
	v_mul_f32_e32 v110, v131, v131
	v_mul_f32_e32 v111, v133, v133
	v_add_f32_e32 v138, v106, v107
	v_fmac_f32_e32 v110, v130, v130
	v_fmac_f32_e32 v111, v132, v132
	ds_read_b128 v[106:109], v238 offset:1024
	v_add_f32_e32 v139, v110, v111
	ds_read_b128 v[110:113], v238 offset:1040
	v_lshl_add_u64 v[118:119], s[36:37], 0, v[118:119]
	v_add_f32_e32 v138, v138, v139
	s_waitcnt lgkmcnt(1)
	v_pk_mul_f32 v[108:109], v[108:109], v[124:125]
	v_pk_mul_f32 v[106:107], v[106:107], v[122:123]
	s_waitcnt lgkmcnt(0)
	v_pk_mul_f32 v[112:113], v[112:113], v[132:133]
	v_pk_mul_f32 v[110:111], v[110:111], v[130:131]
	v_cvt_pk_bf16_f32 v106, v106, v107
	v_cvt_pk_bf16_f32 v107, v108, v109
	v_lshlrev_b32_e32 v122, 16, v162
	v_cvt_pk_bf16_f32 v108, v110, v111
	v_cvt_pk_bf16_f32 v109, v112, v113
	global_store_dwordx4 v[118:119], v[106:109], off nt
	ds_read_b128 v[106:109], v238 offset:512
	ds_read_b128 v[110:113], v238 offset:528
	v_and_b32_e32 v123, 0xffff0000, v162
	v_lshlrev_b32_e32 v124, 16, v163
	v_and_b32_e32 v125, 0xffff0000, v163
	s_waitcnt lgkmcnt(1)
	v_pk_fma_f32 v[100:101], v[100:101], v[108:109], v[124:125]
	v_pk_fma_f32 v[98:99], v[98:99], v[106:107], v[122:123]
	v_lshlrev_b32_e32 v106, 16, v164
	v_and_b32_e32 v107, 0xffff0000, v164
	v_lshlrev_b32_e32 v108, 16, v165
	v_and_b32_e32 v109, 0xffff0000, v165
	s_waitcnt lgkmcnt(0)
	v_pk_fma_f32 v[108:109], v[96:97], v[112:113], v[108:109]
	v_pk_fma_f32 v[96:97], v[94:95], v[110:111], v[106:107]
	v_cvt_pk_bf16_f32 v94, v98, v99
	v_cvt_pk_bf16_f32 v95, v100, v101
	s_nop 0
	v_cvt_pk_bf16_f32 v96, v96, v97
	v_cvt_pk_bf16_f32 v97, v108, v109
	v_and_b32_e32 v107, 0xffff0000, v94
	v_and_b32_e32 v109, 0xffff0000, v95
	global_store_dwordx4 v[120:121], v[94:97], off offset:256 nt
	v_lshlrev_b32_e32 v106, 16, v94
	v_lshlrev_b32_e32 v108, 16, v95
	v_mul_f32_e32 v94, v107, v107
	v_mul_f32_e32 v95, v109, v109
	v_and_b32_e32 v111, 0xffff0000, v96
	v_and_b32_e32 v113, 0xffff0000, v97
	v_fmac_f32_e32 v94, v106, v106
	v_fmac_f32_e32 v95, v108, v108
	v_lshlrev_b32_e32 v110, 16, v96
	v_lshlrev_b32_e32 v112, 16, v97
	v_add_f32_e32 v120, v94, v95
	v_mul_f32_e32 v98, v111, v111
	v_mul_f32_e32 v99, v113, v113
	ds_read_b128 v[94:97], v238 offset:1536
	v_fmac_f32_e32 v98, v110, v110
	v_fmac_f32_e32 v99, v112, v112
	v_add_f32_e32 v121, v98, v99
	v_add_f32_e32 v120, v120, v121
	v_add_f32_e32 v120, v138, v120
	ds_read_b128 v[98:101], v238 offset:1552
	s_waitcnt lgkmcnt(1)
	v_pk_mul_f32 v[94:95], v[94:95], v[106:107]
	ds_swizzle_b32 v106, v120 offset:swizzle(SWAP,16)
	v_pk_mul_f32 v[96:97], v[96:97], v[108:109]
	v_cvt_pk_bf16_f32 v94, v94, v95
	s_waitcnt lgkmcnt(1)
	v_pk_mul_f32 v[100:101], v[100:101], v[112:113]
	v_pk_mul_f32 v[98:99], v[98:99], v[110:111]
	v_cvt_pk_bf16_f32 v95, v96, v97
	s_nop 0
	v_cvt_pk_bf16_f32 v96, v98, v99
	v_cvt_pk_bf16_f32 v97, v100, v101
	global_store_dwordx4 v[118:119], v[94:97], off offset:256 nt
	s_waitcnt lgkmcnt(0)
	s_nop 0
	v_add_f32_e32 v94, v120, v106
	v_mov_b32_e32 v95, v94
	s_nop 1
	v_permlane32_swap_b32_e32 v94, v95
	s_and_saveexec_b64 s[22:23], vcc
	s_cbranch_execz .LBB0_520
	v_add_f32_e32 v94, v94, v95
	v_fma_f32 v94, v94, s74, 0.5
	v_cvt_u32_f32_e32 v94, v94
	global_atomic_add v[146:147], v94, off offset:128
.LBB0_520:
	s_or_b64 exec, exec, s[22:23]
	v_lshlrev_b64 v[94:95], 11, v[224:225]
	v_lshl_add_u64 v[106:107], v[94:95], 0, v[214:215]
	ds_read_b128 v[94:97], v238
	ds_read_b128 v[98:101], v238 offset:16
	v_lshlrev_b32_e32 v108, 16, v158
	v_and_b32_e32 v109, 0xffff0000, v158
	v_lshlrev_b32_e32 v110, 16, v159
	v_and_b32_e32 v111, 0xffff0000, v159
	s_waitcnt lgkmcnt(1)
	v_pk_fma_f32 v[88:89], v[88:89], v[96:97], v[110:111]
	v_pk_fma_f32 v[86:87], v[86:87], v[94:95], v[108:109]
	v_lshlrev_b32_e32 v94, 16, v160
	v_and_b32_e32 v95, 0xffff0000, v160
	v_lshlrev_b32_e32 v96, 16, v161
	v_and_b32_e32 v97, 0xffff0000, v161
	s_waitcnt lgkmcnt(0)
	v_pk_fma_f32 v[96:97], v[84:85], v[100:101], v[96:97]
	v_pk_fma_f32 v[84:85], v[82:83], v[98:99], v[94:95]
	v_lshlrev_b64 v[94:95], 1, v[106:107]
	v_cvt_pk_bf16_f32 v82, v86, v87
	v_cvt_pk_bf16_f32 v83, v88, v89
	v_cvt_pk_bf16_f32 v84, v84, v85
	v_cvt_pk_bf16_f32 v85, v96, v97
	v_lshl_add_u64 v[96:97], s[12:13], 0, v[94:95]
	v_and_b32_e32 v99, 0xffff0000, v82
	v_and_b32_e32 v101, 0xffff0000, v83
	global_store_dwordx4 v[96:97], v[82:85], off nt
	v_lshlrev_b32_e32 v98, 16, v82
	v_lshlrev_b32_e32 v100, 16, v83
	v_and_b32_e32 v107, 0xffff0000, v84
	v_and_b32_e32 v109, 0xffff0000, v85
	v_mul_f32_e32 v82, v99, v99
	v_mul_f32_e32 v83, v101, v101
	v_lshlrev_b32_e32 v106, 16, v84
	v_lshlrev_b32_e32 v108, 16, v85
	v_fmac_f32_e32 v82, v98, v98
	v_fmac_f32_e32 v83, v100, v100
	v_mul_f32_e32 v86, v107, v107
	v_mul_f32_e32 v87, v109, v109
	v_add_f32_e32 v110, v82, v83
	v_fmac_f32_e32 v86, v106, v106
	v_fmac_f32_e32 v87, v108, v108
	ds_read_b128 v[82:85], v238 offset:1024
	v_add_f32_e32 v111, v86, v87
	ds_read_b128 v[86:89], v238 offset:1040
	v_lshl_add_u64 v[94:95], s[36:37], 0, v[94:95]
	v_add_f32_e32 v110, v110, v111
	s_waitcnt lgkmcnt(1)
	v_pk_mul_f32 v[84:85], v[84:85], v[100:101]
	v_pk_mul_f32 v[82:83], v[82:83], v[98:99]
	s_waitcnt lgkmcnt(0)
	v_pk_mul_f32 v[88:89], v[88:89], v[108:109]
	v_pk_mul_f32 v[86:87], v[86:87], v[106:107]
	v_cvt_pk_bf16_f32 v82, v82, v83
	v_cvt_pk_bf16_f32 v83, v84, v85
	v_lshlrev_b32_e32 v98, 16, v154
	v_cvt_pk_bf16_f32 v84, v86, v87
	v_cvt_pk_bf16_f32 v85, v88, v89
	global_store_dwordx4 v[94:95], v[82:85], off nt
	ds_read_b128 v[82:85], v238 offset:512
	ds_read_b128 v[86:89], v238 offset:528
	v_and_b32_e32 v99, 0xffff0000, v154
	v_lshlrev_b32_e32 v100, 16, v155
	v_and_b32_e32 v101, 0xffff0000, v155
	s_waitcnt lgkmcnt(1)
	v_pk_fma_f32 v[76:77], v[76:77], v[84:85], v[100:101]
	v_pk_fma_f32 v[74:75], v[74:75], v[82:83], v[98:99]
	v_lshlrev_b32_e32 v82, 16, v156
	v_and_b32_e32 v83, 0xffff0000, v156
	v_lshlrev_b32_e32 v84, 16, v157
	v_and_b32_e32 v85, 0xffff0000, v157
	s_waitcnt lgkmcnt(0)
	v_pk_fma_f32 v[84:85], v[68:69], v[88:89], v[84:85]
	v_pk_fma_f32 v[68:69], v[66:67], v[86:87], v[82:83]
	v_cvt_pk_bf16_f32 v66, v74, v75
	v_cvt_pk_bf16_f32 v67, v76, v77
	s_nop 0
	v_cvt_pk_bf16_f32 v68, v68, v69
	v_cvt_pk_bf16_f32 v69, v84, v85
	v_and_b32_e32 v83, 0xffff0000, v66
	v_and_b32_e32 v85, 0xffff0000, v67
	global_store_dwordx4 v[96:97], v[66:69], off offset:256 nt
	v_lshlrev_b32_e32 v82, 16, v66
	v_lshlrev_b32_e32 v84, 16, v67
	v_mul_f32_e32 v66, v83, v83
	v_mul_f32_e32 v67, v85, v85
	v_and_b32_e32 v87, 0xffff0000, v68
	v_and_b32_e32 v89, 0xffff0000, v69
	v_fmac_f32_e32 v66, v82, v82
	v_fmac_f32_e32 v67, v84, v84
	v_lshlrev_b32_e32 v86, 16, v68
	v_lshlrev_b32_e32 v88, 16, v69
	v_add_f32_e32 v96, v66, v67
	v_mul_f32_e32 v74, v87, v87
	v_mul_f32_e32 v75, v89, v89
	ds_read_b128 v[66:69], v238 offset:1536
	v_fmac_f32_e32 v74, v86, v86
	v_fmac_f32_e32 v75, v88, v88
	v_add_f32_e32 v97, v74, v75
	v_add_f32_e32 v96, v96, v97
	v_add_f32_e32 v96, v110, v96
	ds_read_b128 v[74:77], v238 offset:1552
	s_waitcnt lgkmcnt(1)
	v_pk_mul_f32 v[66:67], v[66:67], v[82:83]
	ds_swizzle_b32 v82, v96 offset:swizzle(SWAP,16)
	v_pk_mul_f32 v[68:69], v[68:69], v[84:85]
	v_cvt_pk_bf16_f32 v66, v66, v67
	s_waitcnt lgkmcnt(1)
	v_pk_mul_f32 v[76:77], v[76:77], v[88:89]
	v_pk_mul_f32 v[74:75], v[74:75], v[86:87]
	v_cvt_pk_bf16_f32 v67, v68, v69
	s_nop 0
	v_cvt_pk_bf16_f32 v68, v74, v75
	v_cvt_pk_bf16_f32 v69, v76, v77
	global_store_dwordx4 v[94:95], v[66:69], off offset:256 nt
	s_waitcnt lgkmcnt(0)
	s_nop 0
	v_add_f32_e32 v66, v96, v82
	v_mov_b32_e32 v67, v66
	s_nop 1
	v_permlane32_swap_b32_e32 v66, v67
	s_and_saveexec_b64 s[22:23], vcc
	s_cbranch_execz .LBB0_522
	v_add_f32_e32 v66, v66, v67
	v_fma_f32 v66, v66, s74, 0.5
	v_cvt_u32_f32_e32 v66, v66
	global_atomic_add v[146:147], v66, off offset:192
.LBB0_522:
	s_or_b64 exec, exec, s[22:23]
	v_lshlrev_b64 v[66:67], 11, v[222:223]
	v_lshl_add_u64 v[82:83], v[66:67], 0, v[214:215]
	ds_read_b128 v[66:69], v238
	ds_read_b128 v[74:77], v238 offset:16
	v_lshlrev_b32_e32 v84, 16, v142
	v_and_b32_e32 v85, 0xffff0000, v142
	v_lshlrev_b32_e32 v86, 16, v143
	v_and_b32_e32 v87, 0xffff0000, v143
	s_waitcnt lgkmcnt(1)
	v_pk_fma_f32 v[64:65], v[64:65], v[68:69], v[86:87]
	v_pk_fma_f32 v[62:63], v[62:63], v[66:67], v[84:85]
	v_lshlrev_b32_e32 v66, 16, v144
	v_and_b32_e32 v67, 0xffff0000, v144
	v_lshlrev_b32_e32 v68, 16, v145
	v_and_b32_e32 v69, 0xffff0000, v145
	s_waitcnt lgkmcnt(0)
	v_pk_fma_f32 v[68:69], v[60:61], v[76:77], v[68:69]
	v_pk_fma_f32 v[60:61], v[58:59], v[74:75], v[66:67]
	v_lshlrev_b64 v[66:67], 1, v[82:83]
	v_cvt_pk_bf16_f32 v58, v62, v63
	v_cvt_pk_bf16_f32 v59, v64, v65
	v_cvt_pk_bf16_f32 v60, v60, v61
	v_cvt_pk_bf16_f32 v61, v68, v69
	v_lshl_add_u64 v[68:69], s[12:13], 0, v[66:67]
	v_and_b32_e32 v75, 0xffff0000, v58
	v_and_b32_e32 v77, 0xffff0000, v59
	global_store_dwordx4 v[68:69], v[58:61], off nt
	v_lshlrev_b32_e32 v74, 16, v58
	v_lshlrev_b32_e32 v76, 16, v59
	v_and_b32_e32 v83, 0xffff0000, v60
	v_and_b32_e32 v85, 0xffff0000, v61
	v_mul_f32_e32 v58, v75, v75
	v_mul_f32_e32 v59, v77, v77
	v_lshlrev_b32_e32 v82, 16, v60
	v_lshlrev_b32_e32 v84, 16, v61
	v_fmac_f32_e32 v58, v74, v74
	v_fmac_f32_e32 v59, v76, v76
	v_mul_f32_e32 v62, v83, v83
	v_mul_f32_e32 v63, v85, v85
	v_add_f32_e32 v86, v58, v59
	v_fmac_f32_e32 v62, v82, v82
	v_fmac_f32_e32 v63, v84, v84
	ds_read_b128 v[58:61], v238 offset:1024
	v_add_f32_e32 v87, v62, v63
	ds_read_b128 v[62:65], v238 offset:1040
	v_lshl_add_u64 v[66:67], s[36:37], 0, v[66:67]
	v_add_f32_e32 v86, v86, v87
	s_waitcnt lgkmcnt(1)
	v_pk_mul_f32 v[60:61], v[60:61], v[76:77]
	v_pk_mul_f32 v[58:59], v[58:59], v[74:75]
	s_waitcnt lgkmcnt(0)
	v_pk_mul_f32 v[64:65], v[64:65], v[84:85]
	v_pk_mul_f32 v[62:63], v[62:63], v[82:83]
	v_cvt_pk_bf16_f32 v58, v58, v59
	v_cvt_pk_bf16_f32 v59, v60, v61
	v_lshlrev_b32_e32 v74, 16, v134
	v_cvt_pk_bf16_f32 v60, v62, v63
	v_cvt_pk_bf16_f32 v61, v64, v65
	global_store_dwordx4 v[66:67], v[58:61], off nt
	ds_read_b128 v[58:61], v238 offset:512
	ds_read_b128 v[62:65], v238 offset:528
	v_and_b32_e32 v75, 0xffff0000, v134
	v_lshlrev_b32_e32 v76, 16, v135
	v_and_b32_e32 v77, 0xffff0000, v135
	s_waitcnt lgkmcnt(1)
	v_pk_fma_f32 v[56:57], v[56:57], v[60:61], v[76:77]
	v_pk_fma_f32 v[54:55], v[54:55], v[58:59], v[74:75]
	v_lshlrev_b32_e32 v58, 16, v136
	v_and_b32_e32 v59, 0xffff0000, v136
	v_lshlrev_b32_e32 v60, 16, v137
	v_and_b32_e32 v61, 0xffff0000, v137
	s_waitcnt lgkmcnt(0)
	v_pk_fma_f32 v[60:61], v[52:53], v[64:65], v[60:61]
	v_pk_fma_f32 v[52:53], v[50:51], v[62:63], v[58:59]
	v_cvt_pk_bf16_f32 v50, v54, v55
	v_cvt_pk_bf16_f32 v51, v56, v57
	s_nop 0
	v_cvt_pk_bf16_f32 v52, v52, v53
	v_cvt_pk_bf16_f32 v53, v60, v61
	v_and_b32_e32 v59, 0xffff0000, v50
	v_and_b32_e32 v61, 0xffff0000, v51
	global_store_dwordx4 v[68:69], v[50:53], off offset:256 nt
	v_lshlrev_b32_e32 v58, 16, v50
	v_lshlrev_b32_e32 v60, 16, v51
	v_mul_f32_e32 v50, v59, v59
	v_mul_f32_e32 v51, v61, v61
	v_and_b32_e32 v63, 0xffff0000, v52
	v_and_b32_e32 v65, 0xffff0000, v53
	v_fmac_f32_e32 v50, v58, v58
	v_fmac_f32_e32 v51, v60, v60
	v_lshlrev_b32_e32 v62, 16, v52
	v_lshlrev_b32_e32 v64, 16, v53
	v_add_f32_e32 v68, v50, v51
	v_mul_f32_e32 v54, v63, v63
	v_mul_f32_e32 v55, v65, v65
	ds_read_b128 v[50:53], v238 offset:1536
	v_fmac_f32_e32 v54, v62, v62
	v_fmac_f32_e32 v55, v64, v64
	v_add_f32_e32 v69, v54, v55
	v_add_f32_e32 v68, v68, v69
	v_add_f32_e32 v68, v86, v68
	ds_read_b128 v[54:57], v238 offset:1552
	s_waitcnt lgkmcnt(1)
	v_pk_mul_f32 v[50:51], v[50:51], v[58:59]
	ds_swizzle_b32 v58, v68 offset:swizzle(SWAP,16)
	v_pk_mul_f32 v[52:53], v[52:53], v[60:61]
	v_cvt_pk_bf16_f32 v50, v50, v51
	s_waitcnt lgkmcnt(1)
	v_pk_mul_f32 v[56:57], v[56:57], v[64:65]
	v_pk_mul_f32 v[54:55], v[54:55], v[62:63]
	v_cvt_pk_bf16_f32 v51, v52, v53
	s_nop 0
	v_cvt_pk_bf16_f32 v52, v54, v55
	v_cvt_pk_bf16_f32 v53, v56, v57
	global_store_dwordx4 v[66:67], v[50:53], off offset:256 nt
	s_waitcnt lgkmcnt(0)
	s_nop 0
	v_add_f32_e32 v50, v68, v58
	v_mov_b32_e32 v51, v50
	s_nop 1
	v_permlane32_swap_b32_e32 v50, v51
	s_and_saveexec_b64 s[22:23], vcc
	s_cbranch_execz .LBB0_524
	v_add_f32_e32 v50, v50, v51
	v_fma_f32 v50, v50, s74, 0.5
	v_cvt_u32_f32_e32 v50, v50
	global_atomic_add v[146:147], v50, off offset:512
.LBB0_524:
	s_or_b64 exec, exec, s[22:23]
	v_lshlrev_b64 v[50:51], 11, v[220:221]
	v_lshl_add_u64 v[58:59], v[50:51], 0, v[214:215]
	ds_read_b128 v[50:53], v238
	ds_read_b128 v[54:57], v238 offset:16
	v_lshlrev_b32_e32 v60, 16, v126
	v_and_b32_e32 v61, 0xffff0000, v126
	v_lshlrev_b32_e32 v62, 16, v127
	v_and_b32_e32 v63, 0xffff0000, v127
	s_waitcnt lgkmcnt(1)
	v_pk_fma_f32 v[48:49], v[48:49], v[52:53], v[62:63]
	v_pk_fma_f32 v[46:47], v[46:47], v[50:51], v[60:61]
	v_lshlrev_b32_e32 v50, 16, v128
	v_and_b32_e32 v51, 0xffff0000, v128
	v_lshlrev_b32_e32 v52, 16, v129
	v_and_b32_e32 v53, 0xffff0000, v129
	s_waitcnt lgkmcnt(0)
	v_pk_fma_f32 v[52:53], v[44:45], v[56:57], v[52:53]
	v_pk_fma_f32 v[44:45], v[42:43], v[54:55], v[50:51]
	v_lshlrev_b64 v[50:51], 1, v[58:59]
	v_cvt_pk_bf16_f32 v42, v46, v47
	v_cvt_pk_bf16_f32 v43, v48, v49
	v_cvt_pk_bf16_f32 v44, v44, v45
	v_cvt_pk_bf16_f32 v45, v52, v53
	v_lshl_add_u64 v[52:53], s[12:13], 0, v[50:51]
	v_and_b32_e32 v55, 0xffff0000, v42
	v_and_b32_e32 v57, 0xffff0000, v43
	global_store_dwordx4 v[52:53], v[42:45], off nt
	v_lshlrev_b32_e32 v54, 16, v42
	v_lshlrev_b32_e32 v56, 16, v43
	v_and_b32_e32 v59, 0xffff0000, v44
	v_and_b32_e32 v61, 0xffff0000, v45
	v_mul_f32_e32 v42, v55, v55
	v_mul_f32_e32 v43, v57, v57
	v_lshlrev_b32_e32 v58, 16, v44
	v_lshlrev_b32_e32 v60, 16, v45
	v_fmac_f32_e32 v42, v54, v54
	v_fmac_f32_e32 v43, v56, v56
	v_mul_f32_e32 v46, v59, v59
	v_mul_f32_e32 v47, v61, v61
	v_add_f32_e32 v62, v42, v43
	v_fmac_f32_e32 v46, v58, v58
	v_fmac_f32_e32 v47, v60, v60
	ds_read_b128 v[42:45], v238 offset:1024
	v_add_f32_e32 v63, v46, v47
	ds_read_b128 v[46:49], v238 offset:1040
	v_lshl_add_u64 v[50:51], s[36:37], 0, v[50:51]
	v_add_f32_e32 v62, v62, v63
	s_waitcnt lgkmcnt(1)
	v_pk_mul_f32 v[44:45], v[44:45], v[56:57]
	v_pk_mul_f32 v[42:43], v[42:43], v[54:55]
	s_waitcnt lgkmcnt(0)
	v_pk_mul_f32 v[48:49], v[48:49], v[60:61]
	v_pk_mul_f32 v[46:47], v[46:47], v[58:59]
	v_cvt_pk_bf16_f32 v42, v42, v43
	v_cvt_pk_bf16_f32 v43, v44, v45
	v_lshlrev_b32_e32 v54, 16, v114
	v_cvt_pk_bf16_f32 v44, v46, v47
	v_cvt_pk_bf16_f32 v45, v48, v49
	global_store_dwordx4 v[50:51], v[42:45], off nt
	ds_read_b128 v[42:45], v238 offset:512
	ds_read_b128 v[46:49], v238 offset:528
	v_and_b32_e32 v55, 0xffff0000, v114
	v_lshlrev_b32_e32 v56, 16, v115
	v_and_b32_e32 v57, 0xffff0000, v115
	s_waitcnt lgkmcnt(1)
	v_pk_fma_f32 v[40:41], v[40:41], v[44:45], v[56:57]
	v_pk_fma_f32 v[38:39], v[38:39], v[42:43], v[54:55]
	v_lshlrev_b32_e32 v42, 16, v116
	v_and_b32_e32 v43, 0xffff0000, v116
	v_lshlrev_b32_e32 v44, 16, v117
	v_and_b32_e32 v45, 0xffff0000, v117
	s_waitcnt lgkmcnt(0)
	v_pk_fma_f32 v[44:45], v[36:37], v[48:49], v[44:45]
	v_pk_fma_f32 v[36:37], v[34:35], v[46:47], v[42:43]
	v_cvt_pk_bf16_f32 v34, v38, v39
	v_cvt_pk_bf16_f32 v35, v40, v41
	s_nop 0
	v_cvt_pk_bf16_f32 v36, v36, v37
	v_cvt_pk_bf16_f32 v37, v44, v45
	v_and_b32_e32 v43, 0xffff0000, v34
	v_and_b32_e32 v45, 0xffff0000, v35
	global_store_dwordx4 v[52:53], v[34:37], off offset:256 nt
	v_lshlrev_b32_e32 v42, 16, v34
	v_lshlrev_b32_e32 v44, 16, v35
	v_mul_f32_e32 v34, v43, v43
	v_mul_f32_e32 v35, v45, v45
	v_and_b32_e32 v47, 0xffff0000, v36
	v_and_b32_e32 v49, 0xffff0000, v37
	v_fmac_f32_e32 v34, v42, v42
	v_fmac_f32_e32 v35, v44, v44
	v_lshlrev_b32_e32 v46, 16, v36
	v_lshlrev_b32_e32 v48, 16, v37
	v_add_f32_e32 v52, v34, v35
	v_mul_f32_e32 v38, v47, v47
	v_mul_f32_e32 v39, v49, v49
	ds_read_b128 v[34:37], v238 offset:1536
	v_fmac_f32_e32 v38, v46, v46
	v_fmac_f32_e32 v39, v48, v48
	v_add_f32_e32 v53, v38, v39
	v_add_f32_e32 v52, v52, v53
	v_add_f32_e32 v52, v62, v52
	ds_read_b128 v[38:41], v238 offset:1552
	s_waitcnt lgkmcnt(1)
	v_pk_mul_f32 v[34:35], v[34:35], v[42:43]
	ds_swizzle_b32 v42, v52 offset:swizzle(SWAP,16)
	v_pk_mul_f32 v[36:37], v[36:37], v[44:45]
	v_cvt_pk_bf16_f32 v34, v34, v35
	s_waitcnt lgkmcnt(1)
	v_pk_mul_f32 v[40:41], v[40:41], v[48:49]
	v_pk_mul_f32 v[38:39], v[38:39], v[46:47]
	v_cvt_pk_bf16_f32 v35, v36, v37
	s_nop 0
	v_cvt_pk_bf16_f32 v36, v38, v39
	v_cvt_pk_bf16_f32 v37, v40, v41
	global_store_dwordx4 v[50:51], v[34:37], off offset:256 nt
	s_waitcnt lgkmcnt(0)
	s_nop 0
	v_add_f32_e32 v34, v52, v42
	v_mov_b32_e32 v35, v34
	s_nop 1
	v_permlane32_swap_b32_e32 v34, v35
	s_and_saveexec_b64 s[22:23], vcc
	s_cbranch_execz .LBB0_526
	v_add_f32_e32 v34, v34, v35
	v_fma_f32 v34, v34, s74, 0.5
	v_cvt_u32_f32_e32 v34, v34
	global_atomic_add v[146:147], v34, off offset:576
.LBB0_526:
	s_or_b64 exec, exec, s[22:23]
	v_lshlrev_b64 v[34:35], 11, v[218:219]
	v_lshl_add_u64 v[42:43], v[34:35], 0, v[214:215]
	ds_read_b128 v[34:37], v238
	ds_read_b128 v[38:41], v238 offset:16
	v_lshlrev_b32_e32 v44, 16, v102
	v_and_b32_e32 v45, 0xffff0000, v102
	v_lshlrev_b32_e32 v46, 16, v103
	v_and_b32_e32 v47, 0xffff0000, v103
	s_waitcnt lgkmcnt(1)
	v_pk_fma_f32 v[32:33], v[32:33], v[36:37], v[46:47]
	v_pk_fma_f32 v[30:31], v[30:31], v[34:35], v[44:45]
	v_lshlrev_b32_e32 v34, 16, v104
	v_and_b32_e32 v35, 0xffff0000, v104
	v_lshlrev_b32_e32 v36, 16, v105
	v_and_b32_e32 v37, 0xffff0000, v105
	s_waitcnt lgkmcnt(0)
	v_pk_fma_f32 v[36:37], v[28:29], v[40:41], v[36:37]
	v_pk_fma_f32 v[28:29], v[26:27], v[38:39], v[34:35]
	v_lshlrev_b64 v[34:35], 1, v[42:43]
	v_cvt_pk_bf16_f32 v26, v30, v31
	v_cvt_pk_bf16_f32 v27, v32, v33
	v_cvt_pk_bf16_f32 v28, v28, v29
	v_cvt_pk_bf16_f32 v29, v36, v37
	v_lshl_add_u64 v[36:37], s[12:13], 0, v[34:35]
	v_and_b32_e32 v39, 0xffff0000, v26
	v_and_b32_e32 v41, 0xffff0000, v27
	global_store_dwordx4 v[36:37], v[26:29], off nt
	v_lshlrev_b32_e32 v38, 16, v26
	v_lshlrev_b32_e32 v40, 16, v27
	v_and_b32_e32 v43, 0xffff0000, v28
	v_and_b32_e32 v45, 0xffff0000, v29
	v_mul_f32_e32 v26, v39, v39
	v_mul_f32_e32 v27, v41, v41
	v_lshlrev_b32_e32 v42, 16, v28
	v_lshlrev_b32_e32 v44, 16, v29
	v_fmac_f32_e32 v26, v38, v38
	v_fmac_f32_e32 v27, v40, v40
	v_mul_f32_e32 v30, v43, v43
	v_mul_f32_e32 v31, v45, v45
	v_add_f32_e32 v46, v26, v27
	v_fmac_f32_e32 v30, v42, v42
	v_fmac_f32_e32 v31, v44, v44
	ds_read_b128 v[26:29], v238 offset:1024
	v_add_f32_e32 v47, v30, v31
	ds_read_b128 v[30:33], v238 offset:1040
	v_lshl_add_u64 v[34:35], s[36:37], 0, v[34:35]
	v_add_f32_e32 v46, v46, v47
	s_waitcnt lgkmcnt(1)
	v_pk_mul_f32 v[28:29], v[28:29], v[40:41]
	v_pk_mul_f32 v[26:27], v[26:27], v[38:39]
	s_waitcnt lgkmcnt(0)
	v_pk_mul_f32 v[32:33], v[32:33], v[44:45]
	v_pk_mul_f32 v[30:31], v[30:31], v[42:43]
	v_cvt_pk_bf16_f32 v26, v26, v27
	v_cvt_pk_bf16_f32 v27, v28, v29
	v_lshlrev_b32_e32 v38, 16, v90
	v_cvt_pk_bf16_f32 v28, v30, v31
	v_cvt_pk_bf16_f32 v29, v32, v33
	global_store_dwordx4 v[34:35], v[26:29], off nt
	ds_read_b128 v[26:29], v238 offset:512
	ds_read_b128 v[30:33], v238 offset:528
	v_and_b32_e32 v39, 0xffff0000, v90
	v_lshlrev_b32_e32 v40, 16, v91
	v_and_b32_e32 v41, 0xffff0000, v91
	s_waitcnt lgkmcnt(1)
	v_pk_fma_f32 v[24:25], v[24:25], v[28:29], v[40:41]
	v_pk_fma_f32 v[22:23], v[22:23], v[26:27], v[38:39]
	v_lshlrev_b32_e32 v26, 16, v92
	v_and_b32_e32 v27, 0xffff0000, v92
	v_lshlrev_b32_e32 v28, 16, v93
	v_and_b32_e32 v29, 0xffff0000, v93
	s_waitcnt lgkmcnt(0)
	v_pk_fma_f32 v[28:29], v[20:21], v[32:33], v[28:29]
	v_pk_fma_f32 v[20:21], v[18:19], v[30:31], v[26:27]
	v_cvt_pk_bf16_f32 v18, v22, v23
	v_cvt_pk_bf16_f32 v19, v24, v25
	s_nop 0
	v_cvt_pk_bf16_f32 v20, v20, v21
	v_cvt_pk_bf16_f32 v21, v28, v29
	v_and_b32_e32 v27, 0xffff0000, v18
	v_and_b32_e32 v29, 0xffff0000, v19
	global_store_dwordx4 v[36:37], v[18:21], off offset:256 nt
	v_lshlrev_b32_e32 v26, 16, v18
	v_lshlrev_b32_e32 v28, 16, v19
	v_mul_f32_e32 v18, v27, v27
	v_mul_f32_e32 v19, v29, v29
	v_and_b32_e32 v31, 0xffff0000, v20
	v_and_b32_e32 v33, 0xffff0000, v21
	v_fmac_f32_e32 v18, v26, v26
	v_fmac_f32_e32 v19, v28, v28
	v_lshlrev_b32_e32 v30, 16, v20
	v_lshlrev_b32_e32 v32, 16, v21
	v_add_f32_e32 v36, v18, v19
	v_mul_f32_e32 v22, v31, v31
	v_mul_f32_e32 v23, v33, v33
	ds_read_b128 v[18:21], v238 offset:1536
	v_fmac_f32_e32 v22, v30, v30
	v_fmac_f32_e32 v23, v32, v32
	v_add_f32_e32 v37, v22, v23
	v_add_f32_e32 v36, v36, v37
	v_add_f32_e32 v36, v46, v36
	ds_read_b128 v[22:25], v238 offset:1552
	s_waitcnt lgkmcnt(1)
	v_pk_mul_f32 v[18:19], v[18:19], v[26:27]
	ds_swizzle_b32 v26, v36 offset:swizzle(SWAP,16)
	v_pk_mul_f32 v[20:21], v[20:21], v[28:29]
	v_cvt_pk_bf16_f32 v18, v18, v19
	s_waitcnt lgkmcnt(1)
	v_pk_mul_f32 v[24:25], v[24:25], v[32:33]
	v_pk_mul_f32 v[22:23], v[22:23], v[30:31]
	v_cvt_pk_bf16_f32 v19, v20, v21
	s_nop 0
	v_cvt_pk_bf16_f32 v20, v22, v23
	v_cvt_pk_bf16_f32 v21, v24, v25
	global_store_dwordx4 v[34:35], v[18:21], off offset:256 nt
	s_waitcnt lgkmcnt(0)
	s_nop 0
	v_add_f32_e32 v18, v36, v26
	v_mov_b32_e32 v19, v18
	s_nop 1
	v_permlane32_swap_b32_e32 v18, v19
	s_and_saveexec_b64 s[22:23], vcc
	s_cbranch_execz .LBB0_528
	v_add_f32_e32 v18, v18, v19
	v_fma_f32 v18, v18, s74, 0.5
	v_cvt_u32_f32_e32 v18, v18
	global_atomic_add v[146:147], v18, off offset:640
.LBB0_528:
	s_or_b64 exec, exec, s[22:23]
	v_lshlrev_b64 v[18:19], 11, v[216:217]
	v_lshl_add_u64 v[26:27], v[18:19], 0, v[214:215]
	ds_read_b128 v[18:21], v238
	ds_read_b128 v[22:25], v238 offset:16
	v_lshlrev_b32_e32 v28, 16, v78
	v_and_b32_e32 v29, 0xffff0000, v78
	v_lshlrev_b32_e32 v30, 16, v79
	v_and_b32_e32 v31, 0xffff0000, v79
	s_waitcnt lgkmcnt(1)
	v_pk_fma_f32 v[16:17], v[16:17], v[20:21], v[30:31]
	v_pk_fma_f32 v[14:15], v[14:15], v[18:19], v[28:29]
	v_lshlrev_b32_e32 v18, 16, v80
	v_and_b32_e32 v19, 0xffff0000, v80
	v_lshlrev_b32_e32 v20, 16, v81
	v_and_b32_e32 v21, 0xffff0000, v81
	s_waitcnt lgkmcnt(0)
	v_pk_fma_f32 v[20:21], v[12:13], v[24:25], v[20:21]
	v_pk_fma_f32 v[12:13], v[10:11], v[22:23], v[18:19]
	v_lshlrev_b64 v[18:19], 1, v[26:27]
	v_cvt_pk_bf16_f32 v10, v14, v15
	v_cvt_pk_bf16_f32 v11, v16, v17
	v_cvt_pk_bf16_f32 v12, v12, v13
	v_cvt_pk_bf16_f32 v13, v20, v21
	v_lshl_add_u64 v[20:21], s[12:13], 0, v[18:19]
	v_and_b32_e32 v23, 0xffff0000, v10
	v_and_b32_e32 v25, 0xffff0000, v11
	global_store_dwordx4 v[20:21], v[10:13], off nt
	v_lshlrev_b32_e32 v22, 16, v10
	v_lshlrev_b32_e32 v24, 16, v11
	v_and_b32_e32 v27, 0xffff0000, v12
	v_and_b32_e32 v29, 0xffff0000, v13
	v_mul_f32_e32 v10, v23, v23
	v_mul_f32_e32 v11, v25, v25
	v_lshlrev_b32_e32 v26, 16, v12
	v_lshlrev_b32_e32 v28, 16, v13
	v_fmac_f32_e32 v10, v22, v22
	v_fmac_f32_e32 v11, v24, v24
	v_mul_f32_e32 v14, v27, v27
	v_mul_f32_e32 v15, v29, v29
	v_add_f32_e32 v30, v10, v11
	v_fmac_f32_e32 v14, v26, v26
	v_fmac_f32_e32 v15, v28, v28
	ds_read_b128 v[10:13], v238 offset:1024
	v_add_f32_e32 v31, v14, v15
	ds_read_b128 v[14:17], v238 offset:1040
	v_lshl_add_u64 v[18:19], s[36:37], 0, v[18:19]
	v_add_f32_e32 v30, v30, v31
	s_waitcnt lgkmcnt(1)
	v_pk_mul_f32 v[12:13], v[12:13], v[24:25]
	v_pk_mul_f32 v[10:11], v[10:11], v[22:23]
	s_waitcnt lgkmcnt(0)
	v_pk_mul_f32 v[16:17], v[16:17], v[28:29]
	v_pk_mul_f32 v[14:15], v[14:15], v[26:27]
	v_cvt_pk_bf16_f32 v10, v10, v11
	v_cvt_pk_bf16_f32 v11, v12, v13
	v_lshlrev_b32_e32 v22, 16, v70
	v_cvt_pk_bf16_f32 v12, v14, v15
	v_cvt_pk_bf16_f32 v13, v16, v17
	global_store_dwordx4 v[18:19], v[10:13], off nt
	ds_read_b128 v[10:13], v238 offset:512
	ds_read_b128 v[14:17], v238 offset:528
	v_and_b32_e32 v23, 0xffff0000, v70
	v_lshlrev_b32_e32 v24, 16, v71
	v_and_b32_e32 v25, 0xffff0000, v71
	s_waitcnt lgkmcnt(1)
	v_pk_fma_f32 v[8:9], v[8:9], v[12:13], v[24:25]
	v_pk_fma_f32 v[6:7], v[6:7], v[10:11], v[22:23]
	v_lshlrev_b32_e32 v10, 16, v72
	v_and_b32_e32 v11, 0xffff0000, v72
	v_lshlrev_b32_e32 v12, 16, v73
	v_and_b32_e32 v13, 0xffff0000, v73
	s_waitcnt lgkmcnt(0)
	v_pk_fma_f32 v[12:13], v[4:5], v[16:17], v[12:13]
	v_pk_fma_f32 v[4:5], v[2:3], v[14:15], v[10:11]
	v_cvt_pk_bf16_f32 v2, v6, v7
	v_cvt_pk_bf16_f32 v3, v8, v9
	s_nop 0
	v_cvt_pk_bf16_f32 v4, v4, v5
	v_cvt_pk_bf16_f32 v5, v12, v13
	v_and_b32_e32 v11, 0xffff0000, v2
	v_and_b32_e32 v13, 0xffff0000, v3
	global_store_dwordx4 v[20:21], v[2:5], off offset:256 nt
	v_lshlrev_b32_e32 v10, 16, v2
	v_lshlrev_b32_e32 v12, 16, v3
	v_mul_f32_e32 v2, v11, v11
	v_mul_f32_e32 v3, v13, v13
	v_and_b32_e32 v15, 0xffff0000, v4
	v_and_b32_e32 v17, 0xffff0000, v5
	v_fmac_f32_e32 v2, v10, v10
	v_fmac_f32_e32 v3, v12, v12
	v_lshlrev_b32_e32 v14, 16, v4
	v_lshlrev_b32_e32 v16, 16, v5
	v_add_f32_e32 v20, v2, v3
	v_mul_f32_e32 v6, v15, v15
	v_mul_f32_e32 v7, v17, v17
	ds_read_b128 v[2:5], v238 offset:1536
	v_fmac_f32_e32 v6, v14, v14
	v_fmac_f32_e32 v7, v16, v16
	v_add_f32_e32 v21, v6, v7
	v_add_f32_e32 v20, v20, v21
	v_add_f32_e32 v20, v30, v20
	ds_read_b128 v[6:9], v238 offset:1552
	s_waitcnt lgkmcnt(1)
	v_pk_mul_f32 v[2:3], v[2:3], v[10:11]
	ds_swizzle_b32 v10, v20 offset:swizzle(SWAP,16)
	v_pk_mul_f32 v[4:5], v[4:5], v[12:13]
	v_cvt_pk_bf16_f32 v2, v2, v3
	s_waitcnt lgkmcnt(1)
	v_pk_mul_f32 v[8:9], v[8:9], v[16:17]
	v_pk_mul_f32 v[6:7], v[6:7], v[14:15]
	v_cvt_pk_bf16_f32 v3, v4, v5
	s_nop 0
	v_cvt_pk_bf16_f32 v4, v6, v7
	v_cvt_pk_bf16_f32 v5, v8, v9
	global_store_dwordx4 v[18:19], v[2:5], off offset:256 nt
	s_waitcnt lgkmcnt(0)
	s_nop 0
	v_add_f32_e32 v2, v20, v10
	v_mov_b32_e32 v3, v2
	s_nop 1
	v_permlane32_swap_b32_e32 v2, v3
	s_and_saveexec_b64 s[22:23], vcc
	s_cbranch_execz .LBB0_530
	v_add_f32_e32 v2, v2, v3
	v_fma_f32 v2, v2, s74, 0.5
	v_cvt_u32_f32_e32 v2, v2
	global_atomic_add v[146:147], v2, off offset:704

.LBB0_650:
	v_mov_b32_e32 v66, v0
	s_lshl_b32 s0, s22, 8
	s_add_i32 s0, s0, s54
	v_bfe_u32 v240, v66, 4, 2
	v_and_or_b32 v226, v66, 15, s0
	s_or_b32 s0, s6, s67
	v_lshlrev_b32_e32 v66, 3, v240
	v_or_b32_e32 v212, s0, v66
	v_or_b32_e32 v66, s67, v66
	v_ashrrev_i32_e32 v213, 31, v212
	v_ashrrev_i32_e32 v227, 31, v226
	v_lshlrev_b32_e32 v239, 2, v66
	v_lshl_add_u64 v[66:67], v[212:213], 1, s[12:13]
	v_lshlrev_b64 v[68:69], 12, v[226:227]
	v_or_b32_e32 v224, 16, v226
	v_lshl_add_u64 v[68:69], v[66:67], 0, v[68:69]
	v_ashrrev_i32_e32 v225, 31, v224
	global_load_dwordx4 v[228:231], v[68:69], off nt
	global_load_dwordx4 v[186:189], v[68:69], off offset:256 nt
	v_lshlrev_b64 v[68:69], 12, v[224:225]
	v_or_b32_e32 v222, 32, v226
	v_lshl_add_u64 v[68:69], v[66:67], 0, v[68:69]
	v_ashrrev_i32_e32 v223, 31, v222
	global_load_dwordx4 v[182:185], v[68:69], off nt
	global_load_dwordx4 v[178:181], v[68:69], off offset:256 nt
	v_lshlrev_b64 v[68:69], 12, v[222:223]
	v_or_b32_e32 v220, 48, v226
	v_lshl_add_u64 v[68:69], v[66:67], 0, v[68:69]
	v_ashrrev_i32_e32 v221, 31, v220
	global_load_dwordx4 v[174:177], v[68:69], off nt
	global_load_dwordx4 v[170:173], v[68:69], off offset:256 nt
	v_lshlrev_b64 v[68:69], 12, v[220:221]
	v_add_u32_e32 v218, 0x80, v226
	v_lshl_add_u64 v[68:69], v[66:67], 0, v[68:69]
	v_ashrrev_i32_e32 v219, 31, v218
	global_load_dwordx4 v[158:161], v[68:69], off nt
	global_load_dwordx4 v[154:157], v[68:69], off offset:256 nt
	v_lshlrev_b64 v[68:69], 12, v[218:219]
	v_add_u32_e32 v216, 0x90, v226
	v_lshl_add_u64 v[68:69], v[66:67], 0, v[68:69]
	v_ashrrev_i32_e32 v217, 31, v216
	global_load_dwordx4 v[142:145], v[68:69], off nt
	global_load_dwordx4 v[130:133], v[68:69], off offset:256 nt
	v_lshlrev_b64 v[68:69], 12, v[216:217]
	v_add_u32_e32 v214, 0xa0, v226
	v_lshl_add_u64 v[68:69], v[66:67], 0, v[68:69]
	v_ashrrev_i32_e32 v215, 31, v214
	global_load_dwordx4 v[118:121], v[68:69], off nt
	global_load_dwordx4 v[106:109], v[68:69], off offset:256 nt
	v_lshlrev_b64 v[68:69], 12, v[214:215]
	v_add_u32_e32 v210, 0xb0, v226
	v_lshl_add_u64 v[68:69], v[66:67], 0, v[68:69]
	v_ashrrev_i32_e32 v211, 31, v210
	global_load_dwordx4 v[94:97], v[68:69], off nt
	global_load_dwordx4 v[82:85], v[68:69], off offset:256 nt
	v_lshlrev_b64 v[68:69], 12, v[210:211]
	v_lshl_add_u64 v[66:67], v[66:67], 0, v[68:69]
	global_load_dwordx4 v[70:73], v[66:67], off nt
	s_nop 0
	global_load_dwordx4 v[66:69], v[66:67], off offset:256 nt
	v_add_u32_e32 v238, 0, v239
	v_add_u32_e32 v238, 0x24400, v238
	v_lshlrev_b64 v[242:243], 11, v[226:227]
	v_lshl_add_u64 v[250:251], v[242:243], 0, v[212:213]
	ds_read_b128 v[242:245], v238
	ds_read_b128 v[246:249], v238 offset:16
	s_andn2_b64 vcc, exec, s[38:39]
	v_add_u32_e32 v239, s59, v239
	s_waitcnt vmcnt(0)
	v_lshlrev_b32_e32 v252, 16, v228
	v_and_b32_e32 v253, 0xffff0000, v228
	v_lshlrev_b32_e32 v228, 16, v229
	v_and_b32_e32 v229, 0xffff0000, v229
	s_waitcnt lgkmcnt(1)
	v_pk_fma_f32 v[168:169], v[168:169], v[244:245], v[228:229]
	v_lshlrev_b32_e32 v228, 16, v230
	v_and_b32_e32 v229, 0xffff0000, v230
	v_lshlrev_b32_e32 v230, 16, v231
	v_and_b32_e32 v231, 0xffff0000, v231
	v_pk_fma_f32 v[166:167], v[166:167], v[242:243], v[252:253]
	s_waitcnt lgkmcnt(0)
	v_pk_fma_f32 v[164:165], v[164:165], v[248:249], v[230:231]
	v_pk_fma_f32 v[162:163], v[162:163], v[246:247], v[228:229]
	v_cndmask_b32_e64 v230, 0, 1, s[38:39]
	v_cvt_pk_bf16_f32 v242, v166, v167
	v_cvt_pk_bf16_f32 v243, v168, v169
	v_cvt_pk_bf16_f32 v244, v162, v163
	v_cvt_pk_bf16_f32 v245, v164, v165
	v_lshl_add_u64 v[162:163], v[250:251], 1, s[36:37]
	v_lshlrev_b32_e32 v228, 16, v242
	v_and_b32_e32 v229, 0xffff0000, v242
	v_lshlrev_b32_e32 v168, 16, v243
	v_and_b32_e32 v169, 0xffff0000, v243
	v_lshlrev_b32_e32 v166, 16, v244
	v_and_b32_e32 v167, 0xffff0000, v244
	v_lshlrev_b32_e32 v164, 16, v245
	v_and_b32_e32 v165, 0xffff0000, v245
	v_cmp_ne_u32_e64 s[6:7], 1, v230
	v_lshl_add_u64 v[230:231], v[250:251], 1, s[46:47]
	global_store_dwordx4 v[162:163], v[242:245], off nt
	s_cbranch_vccnz .LBB0_652
	ds_read_b128 v[242:245], v239 offset:1024
	ds_read_b128 v[246:249], v239 offset:1040
	s_waitcnt lgkmcnt(1)
	v_pk_mul_f32 v[244:245], v[168:169], v[244:245]
	v_pk_mul_f32 v[242:243], v[228:229], v[242:243]
	s_waitcnt lgkmcnt(0)
	v_pk_mul_f32 v[248:249], v[164:165], v[248:249]
	v_pk_mul_f32 v[246:247], v[166:167], v[246:247]
	v_cvt_pk_bf16_f32 v242, v242, v243
	v_cvt_pk_bf16_f32 v243, v244, v245
	s_nop 0
	v_cvt_pk_bf16_f32 v244, v246, v247
	v_cvt_pk_bf16_f32 v245, v248, v249
	global_store_dwordx4 v[230:231], v[242:245], off nt
.LBB0_652:
	ds_read_b128 v[242:245], v239 offset:512
	ds_read_b128 v[246:249], v239 offset:528
	v_lshlrev_b32_e32 v250, 16, v186
	v_and_b32_e32 v251, 0xffff0000, v186
	v_lshlrev_b32_e32 v186, 16, v187
	v_and_b32_e32 v187, 0xffff0000, v187
	s_waitcnt lgkmcnt(1)
	v_pk_fma_f32 v[152:153], v[152:153], v[244:245], v[186:187]
	v_lshlrev_b32_e32 v186, 16, v188
	v_and_b32_e32 v187, 0xffff0000, v188
	v_lshlrev_b32_e32 v188, 16, v189
	v_and_b32_e32 v189, 0xffff0000, v189
	v_pk_fma_f32 v[150:151], v[150:151], v[242:243], v[250:251]
	s_waitcnt lgkmcnt(0)
	v_pk_fma_f32 v[148:149], v[148:149], v[248:249], v[188:189]
	v_pk_fma_f32 v[146:147], v[146:147], v[246:247], v[186:187]
	v_cvt_pk_bf16_f32 v186, v150, v151
	v_cvt_pk_bf16_f32 v187, v152, v153
	s_and_b64 vcc, exec, s[6:7]
	v_cvt_pk_bf16_f32 v188, v146, v147
	v_cvt_pk_bf16_f32 v189, v148, v149
	v_lshlrev_b32_e32 v152, 16, v186
	v_and_b32_e32 v153, 0xffff0000, v186
	v_lshlrev_b32_e32 v150, 16, v187
	v_and_b32_e32 v151, 0xffff0000, v187
	v_lshlrev_b32_e32 v148, 16, v188
	v_and_b32_e32 v149, 0xffff0000, v188
	v_lshlrev_b32_e32 v146, 16, v189
	v_and_b32_e32 v147, 0xffff0000, v189
	global_store_dwordx4 v[162:163], v[186:189], off offset:256 nt
	s_cbranch_vccnz .LBB0_654
	ds_read_b128 v[186:189], v239 offset:1536
	ds_read_b128 v[242:245], v239 offset:1552
	s_waitcnt lgkmcnt(1)
	v_pk_mul_f32 v[162:163], v[150:151], v[188:189]
	v_pk_mul_f32 v[186:187], v[152:153], v[186:187]
	s_waitcnt lgkmcnt(0)
	v_pk_mul_f32 v[188:189], v[148:149], v[242:243]
	v_pk_mul_f32 v[244:245], v[146:147], v[244:245]
	v_cvt_pk_bf16_f32 v186, v186, v187
	v_cvt_pk_bf16_f32 v187, v162, v163
	v_cvt_pk_bf16_f32 v188, v188, v189
	s_nop 0
	v_cvt_pk_bf16_f32 v189, v244, v245
	global_store_dwordx4 v[230:231], v[186:189], off offset:256 nt

.LBB0_656:
	s_or_b64 exec, exec, s[22:23]
	v_lshlrev_b64 v[146:147], 11, v[224:225]
	v_lshl_add_u64 v[162:163], v[146:147], 0, v[212:213]
	ds_read_b128 v[146:149], v238
	ds_read_b128 v[150:153], v238 offset:16
	v_lshlrev_b32_e32 v164, 16, v182
	v_and_b32_e32 v165, 0xffff0000, v182
	v_lshlrev_b32_e32 v166, 16, v183
	v_and_b32_e32 v167, 0xffff0000, v183
	s_waitcnt lgkmcnt(1)
	v_pk_fma_f32 v[140:141], v[140:141], v[148:149], v[166:167]
	v_pk_fma_f32 v[138:139], v[138:139], v[146:147], v[164:165]
	v_lshlrev_b32_e32 v146, 16, v184
	v_and_b32_e32 v147, 0xffff0000, v184
	v_lshlrev_b32_e32 v148, 16, v185
	v_and_b32_e32 v149, 0xffff0000, v185
	s_waitcnt lgkmcnt(0)
	v_pk_fma_f32 v[136:137], v[136:137], v[152:153], v[148:149]
	v_pk_fma_f32 v[134:135], v[134:135], v[150:151], v[146:147]
	v_cvt_pk_bf16_f32 v150, v138, v139
	v_cvt_pk_bf16_f32 v151, v140, v141
	v_lshl_add_u64 v[148:149], v[162:163], 1, s[36:37]
	v_cvt_pk_bf16_f32 v152, v134, v135
	v_cvt_pk_bf16_f32 v153, v136, v137
	v_lshlrev_b32_e32 v140, 16, v150
	v_and_b32_e32 v141, 0xffff0000, v150
	v_lshlrev_b32_e32 v138, 16, v151
	v_and_b32_e32 v139, 0xffff0000, v151
	v_lshlrev_b32_e32 v136, 16, v152
	v_and_b32_e32 v137, 0xffff0000, v152
	v_lshlrev_b32_e32 v134, 16, v153
	v_and_b32_e32 v135, 0xffff0000, v153
	s_and_b64 vcc, exec, s[6:7]
	v_lshl_add_u64 v[146:147], v[162:163], 1, s[46:47]
	global_store_dwordx4 v[148:149], v[150:153], off nt
	s_cbranch_vccnz .LBB0_658
	ds_read_b128 v[150:153], v239 offset:1024
	ds_read_b128 v[162:165], v239 offset:1040
	s_waitcnt lgkmcnt(1)
	v_pk_mul_f32 v[152:153], v[138:139], v[152:153]
	v_pk_mul_f32 v[150:151], v[140:141], v[150:151]
	s_waitcnt lgkmcnt(0)
	v_pk_mul_f32 v[164:165], v[134:135], v[164:165]
	v_pk_mul_f32 v[162:163], v[136:137], v[162:163]
	v_cvt_pk_bf16_f32 v150, v150, v151
	v_cvt_pk_bf16_f32 v151, v152, v153
	s_nop 0
	v_cvt_pk_bf16_f32 v152, v162, v163
	v_cvt_pk_bf16_f32 v153, v164, v165
	global_store_dwordx4 v[146:147], v[150:153], off nt
.LBB0_658:
	ds_read_b128 v[150:153], v239 offset:512
	ds_read_b128 v[162:165], v239 offset:528
	v_lshlrev_b32_e32 v166, 16, v178
	v_and_b32_e32 v167, 0xffff0000, v178
	v_lshlrev_b32_e32 v168, 16, v179
	v_and_b32_e32 v169, 0xffff0000, v179
	s_waitcnt lgkmcnt(1)
	v_pk_fma_f32 v[128:129], v[128:129], v[152:153], v[168:169]
	v_pk_fma_f32 v[126:127], v[126:127], v[150:151], v[166:167]
	v_lshlrev_b32_e32 v150, 16, v180
	v_and_b32_e32 v151, 0xffff0000, v180
	v_lshlrev_b32_e32 v152, 16, v181
	v_and_b32_e32 v153, 0xffff0000, v181
	s_waitcnt lgkmcnt(0)
	v_pk_fma_f32 v[124:125], v[124:125], v[164:165], v[152:153]
	v_pk_fma_f32 v[122:123], v[122:123], v[162:163], v[150:151]
	v_cvt_pk_bf16_f32 v150, v126, v127
	v_cvt_pk_bf16_f32 v151, v128, v129
	s_and_b64 vcc, exec, s[6:7]
	v_cvt_pk_bf16_f32 v152, v122, v123
	v_cvt_pk_bf16_f32 v153, v124, v125
	v_lshlrev_b32_e32 v128, 16, v150
	v_and_b32_e32 v129, 0xffff0000, v150
	v_lshlrev_b32_e32 v126, 16, v151
	v_and_b32_e32 v127, 0xffff0000, v151
	v_lshlrev_b32_e32 v124, 16, v152
	v_and_b32_e32 v125, 0xffff0000, v152
	v_lshlrev_b32_e32 v122, 16, v153
	v_and_b32_e32 v123, 0xffff0000, v153
	global_store_dwordx4 v[148:149], v[150:153], off offset:256 nt
	s_cbranch_vccnz .LBB0_660
	ds_read_b128 v[148:151], v239 offset:1536
	ds_read_b128 v[162:165], v239 offset:1552
	s_waitcnt lgkmcnt(1)
	v_pk_mul_f32 v[150:151], v[126:127], v[150:151]
	v_pk_mul_f32 v[148:149], v[128:129], v[148:149]
	s_waitcnt lgkmcnt(0)
	v_pk_mul_f32 v[152:153], v[122:123], v[164:165]
	v_pk_mul_f32 v[162:163], v[124:125], v[162:163]
	v_cvt_pk_bf16_f32 v148, v148, v149
	v_cvt_pk_bf16_f32 v149, v150, v151
	s_nop 0
	v_cvt_pk_bf16_f32 v150, v162, v163
	v_cvt_pk_bf16_f32 v151, v152, v153
	global_store_dwordx4 v[146:147], v[148:151], off offset:256 nt

.LBB0_662:
	s_or_b64 exec, exec, s[22:23]
	v_lshlrev_b64 v[122:123], 11, v[222:223]
	v_lshl_add_u64 v[134:135], v[122:123], 0, v[212:213]
	ds_read_b128 v[122:125], v238
	ds_read_b128 v[126:129], v238 offset:16
	v_lshlrev_b32_e32 v136, 16, v174
	v_and_b32_e32 v137, 0xffff0000, v174
	v_lshlrev_b32_e32 v138, 16, v175
	v_and_b32_e32 v139, 0xffff0000, v175
	s_waitcnt lgkmcnt(1)
	v_pk_fma_f32 v[116:117], v[116:117], v[124:125], v[138:139]
	v_pk_fma_f32 v[114:115], v[114:115], v[122:123], v[136:137]
	v_lshlrev_b32_e32 v122, 16, v176
	v_and_b32_e32 v123, 0xffff0000, v176
	v_lshlrev_b32_e32 v124, 16, v177
	v_and_b32_e32 v125, 0xffff0000, v177
	s_waitcnt lgkmcnt(0)
	v_pk_fma_f32 v[112:113], v[112:113], v[128:129], v[124:125]
	v_pk_fma_f32 v[110:111], v[110:111], v[126:127], v[122:123]
	v_cvt_pk_bf16_f32 v126, v114, v115
	v_cvt_pk_bf16_f32 v127, v116, v117
	v_lshl_add_u64 v[124:125], v[134:135], 1, s[36:37]
	v_cvt_pk_bf16_f32 v128, v110, v111
	v_cvt_pk_bf16_f32 v129, v112, v113
	v_lshlrev_b32_e32 v116, 16, v126
	v_and_b32_e32 v117, 0xffff0000, v126
	v_lshlrev_b32_e32 v114, 16, v127
	v_and_b32_e32 v115, 0xffff0000, v127
	v_lshlrev_b32_e32 v112, 16, v128
	v_and_b32_e32 v113, 0xffff0000, v128
	v_lshlrev_b32_e32 v110, 16, v129
	v_and_b32_e32 v111, 0xffff0000, v129
	s_and_b64 vcc, exec, s[6:7]
	v_lshl_add_u64 v[122:123], v[134:135], 1, s[46:47]
	global_store_dwordx4 v[124:125], v[126:129], off nt
	s_cbranch_vccnz .LBB0_664
	ds_read_b128 v[126:129], v239 offset:1024
	ds_read_b128 v[134:137], v239 offset:1040
	s_waitcnt lgkmcnt(1)
	v_pk_mul_f32 v[128:129], v[114:115], v[128:129]
	v_pk_mul_f32 v[126:127], v[116:117], v[126:127]
	s_waitcnt lgkmcnt(0)
	v_pk_mul_f32 v[136:137], v[110:111], v[136:137]
	v_pk_mul_f32 v[134:135], v[112:113], v[134:135]
	v_cvt_pk_bf16_f32 v126, v126, v127
	v_cvt_pk_bf16_f32 v127, v128, v129
	s_nop 0
	v_cvt_pk_bf16_f32 v128, v134, v135
	v_cvt_pk_bf16_f32 v129, v136, v137
	global_store_dwordx4 v[122:123], v[126:129], off nt
.LBB0_664:
	ds_read_b128 v[126:129], v239 offset:512
	ds_read_b128 v[134:137], v239 offset:528
	v_lshlrev_b32_e32 v138, 16, v170
	v_and_b32_e32 v139, 0xffff0000, v170
	v_lshlrev_b32_e32 v140, 16, v171
	v_and_b32_e32 v141, 0xffff0000, v171
	s_waitcnt lgkmcnt(1)
	v_pk_fma_f32 v[104:105], v[104:105], v[128:129], v[140:141]
	v_pk_fma_f32 v[102:103], v[102:103], v[126:127], v[138:139]
	v_lshlrev_b32_e32 v126, 16, v172
	v_and_b32_e32 v127, 0xffff0000, v172
	v_lshlrev_b32_e32 v128, 16, v173
	v_and_b32_e32 v129, 0xffff0000, v173
	s_waitcnt lgkmcnt(0)
	v_pk_fma_f32 v[100:101], v[100:101], v[136:137], v[128:129]
	v_pk_fma_f32 v[98:99], v[98:99], v[134:135], v[126:127]
	v_cvt_pk_bf16_f32 v126, v102, v103
	v_cvt_pk_bf16_f32 v127, v104, v105
	s_and_b64 vcc, exec, s[6:7]
	v_cvt_pk_bf16_f32 v128, v98, v99
	v_cvt_pk_bf16_f32 v129, v100, v101
	v_lshlrev_b32_e32 v104, 16, v126
	v_and_b32_e32 v105, 0xffff0000, v126
	v_lshlrev_b32_e32 v102, 16, v127
	v_and_b32_e32 v103, 0xffff0000, v127
	v_lshlrev_b32_e32 v100, 16, v128
	v_and_b32_e32 v101, 0xffff0000, v128
	v_lshlrev_b32_e32 v98, 16, v129
	v_and_b32_e32 v99, 0xffff0000, v129
	global_store_dwordx4 v[124:125], v[126:129], off offset:256 nt
	s_cbranch_vccnz .LBB0_666
	ds_read_b128 v[124:127], v239 offset:1536
	ds_read_b128 v[134:137], v239 offset:1552
	s_waitcnt lgkmcnt(1)
	v_pk_mul_f32 v[126:127], v[102:103], v[126:127]
	v_pk_mul_f32 v[124:125], v[104:105], v[124:125]
	s_waitcnt lgkmcnt(0)
	v_pk_mul_f32 v[128:129], v[98:99], v[136:137]
	v_pk_mul_f32 v[134:135], v[100:101], v[134:135]
	v_cvt_pk_bf16_f32 v124, v124, v125
	v_cvt_pk_bf16_f32 v125, v126, v127
	s_nop 0
	v_cvt_pk_bf16_f32 v126, v134, v135
	v_cvt_pk_bf16_f32 v127, v128, v129
	global_store_dwordx4 v[122:123], v[124:127], off offset:256 nt

.LBB0_668:
	s_or_b64 exec, exec, s[22:23]
	v_lshlrev_b64 v[98:99], 11, v[220:221]
	v_lshl_add_u64 v[110:111], v[98:99], 0, v[212:213]
	ds_read_b128 v[98:101], v238
	ds_read_b128 v[102:105], v238 offset:16
	v_lshlrev_b32_e32 v112, 16, v158
	v_and_b32_e32 v113, 0xffff0000, v158
	v_lshlrev_b32_e32 v114, 16, v159
	v_and_b32_e32 v115, 0xffff0000, v159
	s_waitcnt lgkmcnt(1)
	v_pk_fma_f32 v[92:93], v[92:93], v[100:101], v[114:115]
	v_pk_fma_f32 v[90:91], v[90:91], v[98:99], v[112:113]
	v_lshlrev_b32_e32 v98, 16, v160
	v_and_b32_e32 v99, 0xffff0000, v160
	v_lshlrev_b32_e32 v100, 16, v161
	v_and_b32_e32 v101, 0xffff0000, v161
	s_waitcnt lgkmcnt(0)
	v_pk_fma_f32 v[88:89], v[88:89], v[104:105], v[100:101]
	v_pk_fma_f32 v[86:87], v[86:87], v[102:103], v[98:99]
	v_cvt_pk_bf16_f32 v102, v90, v91
	v_cvt_pk_bf16_f32 v103, v92, v93
	v_lshl_add_u64 v[100:101], v[110:111], 1, s[36:37]
	v_cvt_pk_bf16_f32 v104, v86, v87
	v_cvt_pk_bf16_f32 v105, v88, v89
	v_lshlrev_b32_e32 v92, 16, v102
	v_and_b32_e32 v93, 0xffff0000, v102
	v_lshlrev_b32_e32 v90, 16, v103
	v_and_b32_e32 v91, 0xffff0000, v103
	v_lshlrev_b32_e32 v88, 16, v104
	v_and_b32_e32 v89, 0xffff0000, v104
	v_lshlrev_b32_e32 v86, 16, v105
	v_and_b32_e32 v87, 0xffff0000, v105
	s_and_b64 vcc, exec, s[6:7]
	v_lshl_add_u64 v[98:99], v[110:111], 1, s[46:47]
	global_store_dwordx4 v[100:101], v[102:105], off nt
	s_cbranch_vccnz .LBB0_670
	ds_read_b128 v[102:105], v239 offset:1024
	ds_read_b128 v[110:113], v239 offset:1040
	s_waitcnt lgkmcnt(1)
	v_pk_mul_f32 v[104:105], v[90:91], v[104:105]
	v_pk_mul_f32 v[102:103], v[92:93], v[102:103]
	s_waitcnt lgkmcnt(0)
	v_pk_mul_f32 v[112:113], v[86:87], v[112:113]
	v_pk_mul_f32 v[110:111], v[88:89], v[110:111]
	v_cvt_pk_bf16_f32 v102, v102, v103
	v_cvt_pk_bf16_f32 v103, v104, v105
	s_nop 0
	v_cvt_pk_bf16_f32 v104, v110, v111
	v_cvt_pk_bf16_f32 v105, v112, v113
	global_store_dwordx4 v[98:99], v[102:105], off nt
.LBB0_670:
	ds_read_b128 v[102:105], v239 offset:512
	ds_read_b128 v[110:113], v239 offset:528
	v_lshlrev_b32_e32 v114, 16, v154
	v_and_b32_e32 v115, 0xffff0000, v154
	v_lshlrev_b32_e32 v116, 16, v155
	v_and_b32_e32 v117, 0xffff0000, v155
	s_waitcnt lgkmcnt(1)
	v_pk_fma_f32 v[80:81], v[80:81], v[104:105], v[116:117]
	v_pk_fma_f32 v[78:79], v[78:79], v[102:103], v[114:115]
	v_lshlrev_b32_e32 v102, 16, v156
	v_and_b32_e32 v103, 0xffff0000, v156
	v_lshlrev_b32_e32 v104, 16, v157
	v_and_b32_e32 v105, 0xffff0000, v157
	s_waitcnt lgkmcnt(0)
	v_pk_fma_f32 v[76:77], v[76:77], v[112:113], v[104:105]
	v_pk_fma_f32 v[74:75], v[74:75], v[110:111], v[102:103]
	v_cvt_pk_bf16_f32 v102, v78, v79
	v_cvt_pk_bf16_f32 v103, v80, v81
	s_and_b64 vcc, exec, s[6:7]
	v_cvt_pk_bf16_f32 v104, v74, v75
	v_cvt_pk_bf16_f32 v105, v76, v77
	v_lshlrev_b32_e32 v80, 16, v102
	v_and_b32_e32 v81, 0xffff0000, v102
	v_lshlrev_b32_e32 v78, 16, v103
	v_and_b32_e32 v79, 0xffff0000, v103
	v_lshlrev_b32_e32 v76, 16, v104
	v_and_b32_e32 v77, 0xffff0000, v104
	v_lshlrev_b32_e32 v74, 16, v105
	v_and_b32_e32 v75, 0xffff0000, v105
	global_store_dwordx4 v[100:101], v[102:105], off offset:256 nt
	s_cbranch_vccnz .LBB0_672
	ds_read_b128 v[100:103], v239 offset:1536
	ds_read_b128 v[110:113], v239 offset:1552
	s_waitcnt lgkmcnt(1)
	v_pk_mul_f32 v[102:103], v[78:79], v[102:103]
	v_pk_mul_f32 v[100:101], v[80:81], v[100:101]
	s_waitcnt lgkmcnt(0)
	v_pk_mul_f32 v[104:105], v[74:75], v[112:113]
	v_pk_mul_f32 v[110:111], v[76:77], v[110:111]
	v_cvt_pk_bf16_f32 v100, v100, v101
	v_cvt_pk_bf16_f32 v101, v102, v103
	s_nop 0
	v_cvt_pk_bf16_f32 v102, v110, v111
	v_cvt_pk_bf16_f32 v103, v104, v105
	global_store_dwordx4 v[98:99], v[100:103], off offset:256 nt

.LBB0_674:
	s_or_b64 exec, exec, s[22:23]
	v_lshlrev_b64 v[74:75], 11, v[218:219]
	v_lshl_add_u64 v[86:87], v[74:75], 0, v[212:213]
	ds_read_b128 v[74:77], v238
	ds_read_b128 v[78:81], v238 offset:16
	v_lshlrev_b32_e32 v88, 16, v142
	v_and_b32_e32 v89, 0xffff0000, v142
	v_lshlrev_b32_e32 v90, 16, v143
	v_and_b32_e32 v91, 0xffff0000, v143
	s_waitcnt lgkmcnt(1)
	v_pk_fma_f32 v[64:65], v[64:65], v[76:77], v[90:91]
	v_pk_fma_f32 v[62:63], v[62:63], v[74:75], v[88:89]
	v_lshlrev_b32_e32 v74, 16, v144
	v_and_b32_e32 v75, 0xffff0000, v144
	v_lshlrev_b32_e32 v76, 16, v145
	v_and_b32_e32 v77, 0xffff0000, v145
	s_waitcnt lgkmcnt(0)
	v_pk_fma_f32 v[60:61], v[60:61], v[80:81], v[76:77]
	v_pk_fma_f32 v[58:59], v[58:59], v[78:79], v[74:75]
	v_cvt_pk_bf16_f32 v78, v62, v63
	v_cvt_pk_bf16_f32 v79, v64, v65
	v_lshl_add_u64 v[76:77], v[86:87], 1, s[36:37]
	v_cvt_pk_bf16_f32 v80, v58, v59
	v_cvt_pk_bf16_f32 v81, v60, v61
	v_lshlrev_b32_e32 v64, 16, v78
	v_and_b32_e32 v65, 0xffff0000, v78
	v_lshlrev_b32_e32 v62, 16, v79
	v_and_b32_e32 v63, 0xffff0000, v79
	v_lshlrev_b32_e32 v60, 16, v80
	v_and_b32_e32 v61, 0xffff0000, v80
	v_lshlrev_b32_e32 v58, 16, v81
	v_and_b32_e32 v59, 0xffff0000, v81
	s_and_b64 vcc, exec, s[6:7]
	v_lshl_add_u64 v[74:75], v[86:87], 1, s[46:47]
	global_store_dwordx4 v[76:77], v[78:81], off nt
	s_cbranch_vccnz .LBB0_676
	ds_read_b128 v[78:81], v239 offset:1024
	ds_read_b128 v[86:89], v239 offset:1040
	s_waitcnt lgkmcnt(1)
	v_pk_mul_f32 v[80:81], v[62:63], v[80:81]
	v_pk_mul_f32 v[78:79], v[64:65], v[78:79]
	s_waitcnt lgkmcnt(0)
	v_pk_mul_f32 v[88:89], v[58:59], v[88:89]
	v_pk_mul_f32 v[86:87], v[60:61], v[86:87]
	v_cvt_pk_bf16_f32 v78, v78, v79
	v_cvt_pk_bf16_f32 v79, v80, v81
	s_nop 0
	v_cvt_pk_bf16_f32 v80, v86, v87
	v_cvt_pk_bf16_f32 v81, v88, v89
	global_store_dwordx4 v[74:75], v[78:81], off nt
.LBB0_676:
	ds_read_b128 v[78:81], v239 offset:512
	ds_read_b128 v[86:89], v239 offset:528
	v_lshlrev_b32_e32 v90, 16, v130
	v_and_b32_e32 v91, 0xffff0000, v130
	v_lshlrev_b32_e32 v92, 16, v131
	v_and_b32_e32 v93, 0xffff0000, v131
	s_waitcnt lgkmcnt(1)
	v_pk_fma_f32 v[56:57], v[56:57], v[80:81], v[92:93]
	v_pk_fma_f32 v[54:55], v[54:55], v[78:79], v[90:91]
	v_lshlrev_b32_e32 v78, 16, v132
	v_and_b32_e32 v79, 0xffff0000, v132
	v_lshlrev_b32_e32 v80, 16, v133
	v_and_b32_e32 v81, 0xffff0000, v133
	s_waitcnt lgkmcnt(0)
	v_pk_fma_f32 v[52:53], v[52:53], v[88:89], v[80:81]
	v_pk_fma_f32 v[50:51], v[50:51], v[86:87], v[78:79]
	v_cvt_pk_bf16_f32 v78, v54, v55
	v_cvt_pk_bf16_f32 v79, v56, v57
	s_and_b64 vcc, exec, s[6:7]
	v_cvt_pk_bf16_f32 v80, v50, v51
	v_cvt_pk_bf16_f32 v81, v52, v53
	v_lshlrev_b32_e32 v56, 16, v78
	v_and_b32_e32 v57, 0xffff0000, v78
	v_lshlrev_b32_e32 v54, 16, v79
	v_and_b32_e32 v55, 0xffff0000, v79
	v_lshlrev_b32_e32 v52, 16, v80
	v_and_b32_e32 v53, 0xffff0000, v80
	v_lshlrev_b32_e32 v50, 16, v81
	v_and_b32_e32 v51, 0xffff0000, v81
	global_store_dwordx4 v[76:77], v[78:81], off offset:256 nt
	s_cbranch_vccnz .LBB0_678
	ds_read_b128 v[76:79], v239 offset:1536
	ds_read_b128 v[86:89], v239 offset:1552
	s_waitcnt lgkmcnt(1)
	v_pk_mul_f32 v[78:79], v[54:55], v[78:79]
	v_pk_mul_f32 v[76:77], v[56:57], v[76:77]
	s_waitcnt lgkmcnt(0)
	v_pk_mul_f32 v[80:81], v[50:51], v[88:89]
	v_pk_mul_f32 v[86:87], v[52:53], v[86:87]
	v_cvt_pk_bf16_f32 v76, v76, v77
	v_cvt_pk_bf16_f32 v77, v78, v79
	s_nop 0
	v_cvt_pk_bf16_f32 v78, v86, v87
	v_cvt_pk_bf16_f32 v79, v80, v81
	global_store_dwordx4 v[74:75], v[76:79], off offset:256 nt

.LBB0_680:
	s_or_b64 exec, exec, s[22:23]
	v_lshlrev_b64 v[50:51], 11, v[216:217]
	v_lshl_add_u64 v[58:59], v[50:51], 0, v[212:213]
	ds_read_b128 v[50:53], v238
	ds_read_b128 v[54:57], v238 offset:16
	v_lshlrev_b32_e32 v60, 16, v118
	v_and_b32_e32 v61, 0xffff0000, v118
	v_lshlrev_b32_e32 v62, 16, v119
	v_and_b32_e32 v63, 0xffff0000, v119
	s_waitcnt lgkmcnt(1)
	v_pk_fma_f32 v[48:49], v[48:49], v[52:53], v[62:63]
	v_pk_fma_f32 v[46:47], v[46:47], v[50:51], v[60:61]
	v_lshlrev_b32_e32 v50, 16, v120
	v_and_b32_e32 v51, 0xffff0000, v120
	v_lshlrev_b32_e32 v52, 16, v121
	v_and_b32_e32 v53, 0xffff0000, v121
	s_waitcnt lgkmcnt(0)
	v_pk_fma_f32 v[44:45], v[44:45], v[56:57], v[52:53]
	v_pk_fma_f32 v[42:43], v[42:43], v[54:55], v[50:51]
	v_cvt_pk_bf16_f32 v54, v46, v47
	v_cvt_pk_bf16_f32 v55, v48, v49
	v_lshl_add_u64 v[52:53], v[58:59], 1, s[36:37]
	v_cvt_pk_bf16_f32 v56, v42, v43
	v_cvt_pk_bf16_f32 v57, v44, v45
	v_lshlrev_b32_e32 v48, 16, v54
	v_and_b32_e32 v49, 0xffff0000, v54
	v_lshlrev_b32_e32 v46, 16, v55
	v_and_b32_e32 v47, 0xffff0000, v55
	v_lshlrev_b32_e32 v44, 16, v56
	v_and_b32_e32 v45, 0xffff0000, v56
	v_lshlrev_b32_e32 v42, 16, v57
	v_and_b32_e32 v43, 0xffff0000, v57
	s_and_b64 vcc, exec, s[6:7]
	v_lshl_add_u64 v[50:51], v[58:59], 1, s[46:47]
	global_store_dwordx4 v[52:53], v[54:57], off nt
	s_cbranch_vccnz .LBB0_682
	ds_read_b128 v[54:57], v239 offset:1024
	ds_read_b128 v[58:61], v239 offset:1040
	s_waitcnt lgkmcnt(1)
	v_pk_mul_f32 v[56:57], v[46:47], v[56:57]
	v_pk_mul_f32 v[54:55], v[48:49], v[54:55]
	s_waitcnt lgkmcnt(0)
	v_pk_mul_f32 v[60:61], v[42:43], v[60:61]
	v_pk_mul_f32 v[58:59], v[44:45], v[58:59]
	v_cvt_pk_bf16_f32 v54, v54, v55
	v_cvt_pk_bf16_f32 v55, v56, v57
	s_nop 0
	v_cvt_pk_bf16_f32 v56, v58, v59
	v_cvt_pk_bf16_f32 v57, v60, v61
	global_store_dwordx4 v[50:51], v[54:57], off nt
.LBB0_682:
	ds_read_b128 v[54:57], v239 offset:512
	ds_read_b128 v[58:61], v239 offset:528
	v_lshlrev_b32_e32 v62, 16, v106
	v_and_b32_e32 v63, 0xffff0000, v106
	v_lshlrev_b32_e32 v64, 16, v107
	v_and_b32_e32 v65, 0xffff0000, v107
	s_waitcnt lgkmcnt(1)
	v_pk_fma_f32 v[40:41], v[40:41], v[56:57], v[64:65]
	v_pk_fma_f32 v[38:39], v[38:39], v[54:55], v[62:63]
	v_lshlrev_b32_e32 v54, 16, v108
	v_and_b32_e32 v55, 0xffff0000, v108
	v_lshlrev_b32_e32 v56, 16, v109
	v_and_b32_e32 v57, 0xffff0000, v109
	s_waitcnt lgkmcnt(0)
	v_pk_fma_f32 v[36:37], v[36:37], v[60:61], v[56:57]
	v_pk_fma_f32 v[34:35], v[34:35], v[58:59], v[54:55]
	v_cvt_pk_bf16_f32 v54, v38, v39
	v_cvt_pk_bf16_f32 v55, v40, v41
	s_and_b64 vcc, exec, s[6:7]
	v_cvt_pk_bf16_f32 v56, v34, v35
	v_cvt_pk_bf16_f32 v57, v36, v37
	v_lshlrev_b32_e32 v40, 16, v54
	v_and_b32_e32 v41, 0xffff0000, v54
	v_lshlrev_b32_e32 v38, 16, v55
	v_and_b32_e32 v39, 0xffff0000, v55
	v_lshlrev_b32_e32 v36, 16, v56
	v_and_b32_e32 v37, 0xffff0000, v56
	v_lshlrev_b32_e32 v34, 16, v57
	v_and_b32_e32 v35, 0xffff0000, v57
	global_store_dwordx4 v[52:53], v[54:57], off offset:256 nt
	s_cbranch_vccnz .LBB0_684
	ds_read_b128 v[52:55], v239 offset:1536
	ds_read_b128 v[56:59], v239 offset:1552
	s_waitcnt lgkmcnt(1)
	v_pk_mul_f32 v[54:55], v[38:39], v[54:55]
	v_pk_mul_f32 v[52:53], v[40:41], v[52:53]
	s_waitcnt lgkmcnt(0)
	v_pk_mul_f32 v[58:59], v[34:35], v[58:59]
	v_pk_mul_f32 v[56:57], v[36:37], v[56:57]
	v_cvt_pk_bf16_f32 v52, v52, v53
	v_cvt_pk_bf16_f32 v53, v54, v55
	s_nop 0
	v_cvt_pk_bf16_f32 v54, v56, v57
	v_cvt_pk_bf16_f32 v55, v58, v59
	global_store_dwordx4 v[50:51], v[52:55], off offset:256 nt

.LBB0_686:
	s_or_b64 exec, exec, s[22:23]
	v_lshlrev_b64 v[34:35], 11, v[214:215]
	v_lshl_add_u64 v[42:43], v[34:35], 0, v[212:213]
	ds_read_b128 v[34:37], v238
	ds_read_b128 v[38:41], v238 offset:16
	v_lshlrev_b32_e32 v44, 16, v94
	v_and_b32_e32 v45, 0xffff0000, v94
	v_lshlrev_b32_e32 v46, 16, v95
	v_and_b32_e32 v47, 0xffff0000, v95
	s_waitcnt lgkmcnt(1)
	v_pk_fma_f32 v[32:33], v[32:33], v[36:37], v[46:47]
	v_pk_fma_f32 v[30:31], v[30:31], v[34:35], v[44:45]
	v_lshlrev_b32_e32 v34, 16, v96
	v_and_b32_e32 v35, 0xffff0000, v96
	v_lshlrev_b32_e32 v36, 16, v97
	v_and_b32_e32 v37, 0xffff0000, v97
	s_waitcnt lgkmcnt(0)
	v_pk_fma_f32 v[28:29], v[28:29], v[40:41], v[36:37]
	v_pk_fma_f32 v[26:27], v[26:27], v[38:39], v[34:35]
	v_cvt_pk_bf16_f32 v38, v30, v31
	v_cvt_pk_bf16_f32 v39, v32, v33
	v_lshl_add_u64 v[36:37], v[42:43], 1, s[36:37]
	v_cvt_pk_bf16_f32 v40, v26, v27
	v_cvt_pk_bf16_f32 v41, v28, v29
	v_lshlrev_b32_e32 v32, 16, v38
	v_and_b32_e32 v33, 0xffff0000, v38
	v_lshlrev_b32_e32 v30, 16, v39
	v_and_b32_e32 v31, 0xffff0000, v39
	v_lshlrev_b32_e32 v28, 16, v40
	v_and_b32_e32 v29, 0xffff0000, v40
	v_lshlrev_b32_e32 v26, 16, v41
	v_and_b32_e32 v27, 0xffff0000, v41
	s_and_b64 vcc, exec, s[6:7]
	v_lshl_add_u64 v[34:35], v[42:43], 1, s[46:47]
	global_store_dwordx4 v[36:37], v[38:41], off nt
	s_cbranch_vccnz .LBB0_688
	ds_read_b128 v[38:41], v239 offset:1024
	ds_read_b128 v[42:45], v239 offset:1040
	s_waitcnt lgkmcnt(1)
	v_pk_mul_f32 v[40:41], v[30:31], v[40:41]
	v_pk_mul_f32 v[38:39], v[32:33], v[38:39]
	s_waitcnt lgkmcnt(0)
	v_pk_mul_f32 v[44:45], v[26:27], v[44:45]
	v_pk_mul_f32 v[42:43], v[28:29], v[42:43]
	v_cvt_pk_bf16_f32 v38, v38, v39
	v_cvt_pk_bf16_f32 v39, v40, v41
	s_nop 0
	v_cvt_pk_bf16_f32 v40, v42, v43
	v_cvt_pk_bf16_f32 v41, v44, v45
	global_store_dwordx4 v[34:35], v[38:41], off nt
.LBB0_688:
	ds_read_b128 v[38:41], v239 offset:512
	ds_read_b128 v[42:45], v239 offset:528
	v_lshlrev_b32_e32 v46, 16, v82
	v_and_b32_e32 v47, 0xffff0000, v82
	v_lshlrev_b32_e32 v48, 16, v83
	v_and_b32_e32 v49, 0xffff0000, v83
	s_waitcnt lgkmcnt(1)
	v_pk_fma_f32 v[24:25], v[24:25], v[40:41], v[48:49]
	v_pk_fma_f32 v[22:23], v[22:23], v[38:39], v[46:47]
	v_lshlrev_b32_e32 v38, 16, v84
	v_and_b32_e32 v39, 0xffff0000, v84
	v_lshlrev_b32_e32 v40, 16, v85
	v_and_b32_e32 v41, 0xffff0000, v85
	s_waitcnt lgkmcnt(0)
	v_pk_fma_f32 v[20:21], v[20:21], v[44:45], v[40:41]
	v_pk_fma_f32 v[18:19], v[18:19], v[42:43], v[38:39]
	v_cvt_pk_bf16_f32 v38, v22, v23
	v_cvt_pk_bf16_f32 v39, v24, v25
	s_and_b64 vcc, exec, s[6:7]
	v_cvt_pk_bf16_f32 v40, v18, v19
	v_cvt_pk_bf16_f32 v41, v20, v21
	v_lshlrev_b32_e32 v24, 16, v38
	v_and_b32_e32 v25, 0xffff0000, v38
	v_lshlrev_b32_e32 v22, 16, v39
	v_and_b32_e32 v23, 0xffff0000, v39
	v_lshlrev_b32_e32 v20, 16, v40
	v_and_b32_e32 v21, 0xffff0000, v40
	v_lshlrev_b32_e32 v18, 16, v41
	v_and_b32_e32 v19, 0xffff0000, v41
	global_store_dwordx4 v[36:37], v[38:41], off offset:256 nt
	s_cbranch_vccnz .LBB0_690
	ds_read_b128 v[36:39], v239 offset:1536
	ds_read_b128 v[40:43], v239 offset:1552
	s_waitcnt lgkmcnt(1)
	v_pk_mul_f32 v[38:39], v[22:23], v[38:39]
	v_pk_mul_f32 v[36:37], v[24:25], v[36:37]
	s_waitcnt lgkmcnt(0)
	v_pk_mul_f32 v[42:43], v[18:19], v[42:43]
	v_pk_mul_f32 v[40:41], v[20:21], v[40:41]
	v_cvt_pk_bf16_f32 v36, v36, v37
	v_cvt_pk_bf16_f32 v37, v38, v39
	s_nop 0
	v_cvt_pk_bf16_f32 v38, v40, v41
	v_cvt_pk_bf16_f32 v39, v42, v43
	global_store_dwordx4 v[34:35], v[36:39], off offset:256 nt

.LBB0_692:
	s_or_b64 exec, exec, s[22:23]
	v_lshlrev_b64 v[18:19], 11, v[210:211]
	v_lshl_add_u64 v[26:27], v[18:19], 0, v[212:213]
	ds_read_b128 v[18:21], v238
	ds_read_b128 v[22:25], v238 offset:16
	v_lshlrev_b32_e32 v28, 16, v70
	v_and_b32_e32 v29, 0xffff0000, v70
	v_lshlrev_b32_e32 v30, 16, v71
	v_and_b32_e32 v31, 0xffff0000, v71
	s_waitcnt lgkmcnt(1)
	v_pk_fma_f32 v[16:17], v[16:17], v[20:21], v[30:31]
	v_pk_fma_f32 v[14:15], v[14:15], v[18:19], v[28:29]
	v_lshlrev_b32_e32 v18, 16, v72
	v_and_b32_e32 v19, 0xffff0000, v72
	v_lshlrev_b32_e32 v20, 16, v73
	v_and_b32_e32 v21, 0xffff0000, v73
	s_waitcnt lgkmcnt(0)
	v_pk_fma_f32 v[12:13], v[12:13], v[24:25], v[20:21]
	v_pk_fma_f32 v[10:11], v[10:11], v[22:23], v[18:19]
	v_cvt_pk_bf16_f32 v22, v14, v15
	v_cvt_pk_bf16_f32 v23, v16, v17
	v_lshl_add_u64 v[20:21], v[26:27], 1, s[36:37]
	v_cvt_pk_bf16_f32 v24, v10, v11
	v_cvt_pk_bf16_f32 v25, v12, v13
	v_lshlrev_b32_e32 v16, 16, v22
	v_and_b32_e32 v17, 0xffff0000, v22
	v_lshlrev_b32_e32 v14, 16, v23
	v_and_b32_e32 v15, 0xffff0000, v23
	v_lshlrev_b32_e32 v12, 16, v24
	v_and_b32_e32 v13, 0xffff0000, v24
	v_lshlrev_b32_e32 v10, 16, v25
	v_and_b32_e32 v11, 0xffff0000, v25
	s_and_b64 vcc, exec, s[6:7]
	v_lshl_add_u64 v[18:19], v[26:27], 1, s[46:47]
	global_store_dwordx4 v[20:21], v[22:25], off nt
	s_cbranch_vccnz .LBB0_694
	ds_read_b128 v[22:25], v239 offset:1024
	ds_read_b128 v[26:29], v239 offset:1040
	s_waitcnt lgkmcnt(1)
	v_pk_mul_f32 v[24:25], v[14:15], v[24:25]
	v_pk_mul_f32 v[22:23], v[16:17], v[22:23]
	s_waitcnt lgkmcnt(0)
	v_pk_mul_f32 v[28:29], v[10:11], v[28:29]
	v_pk_mul_f32 v[26:27], v[12:13], v[26:27]
	v_cvt_pk_bf16_f32 v22, v22, v23
	v_cvt_pk_bf16_f32 v23, v24, v25
	s_nop 0
	v_cvt_pk_bf16_f32 v24, v26, v27
	v_cvt_pk_bf16_f32 v25, v28, v29
	global_store_dwordx4 v[18:19], v[22:25], off nt
.LBB0_694:
	ds_read_b128 v[22:25], v239 offset:512
	ds_read_b128 v[26:29], v239 offset:528
	v_lshlrev_b32_e32 v30, 16, v66
	v_and_b32_e32 v31, 0xffff0000, v66
	v_lshlrev_b32_e32 v32, 16, v67
	v_and_b32_e32 v33, 0xffff0000, v67
	s_waitcnt lgkmcnt(1)
	v_pk_fma_f32 v[8:9], v[8:9], v[24:25], v[32:33]
	v_pk_fma_f32 v[6:7], v[6:7], v[22:23], v[30:31]
	v_lshlrev_b32_e32 v22, 16, v68
	v_and_b32_e32 v23, 0xffff0000, v68
	v_lshlrev_b32_e32 v24, 16, v69
	v_and_b32_e32 v25, 0xffff0000, v69
	s_waitcnt lgkmcnt(0)
	v_pk_fma_f32 v[4:5], v[4:5], v[28:29], v[24:25]
	v_pk_fma_f32 v[2:3], v[2:3], v[26:27], v[22:23]
	v_cvt_pk_bf16_f32 v22, v6, v7
	v_cvt_pk_bf16_f32 v23, v8, v9
	s_and_b64 vcc, exec, s[6:7]
	v_cvt_pk_bf16_f32 v24, v2, v3
	v_cvt_pk_bf16_f32 v25, v4, v5
	v_lshlrev_b32_e32 v8, 16, v22
	v_and_b32_e32 v9, 0xffff0000, v22
	v_lshlrev_b32_e32 v6, 16, v23
	v_and_b32_e32 v7, 0xffff0000, v23
	v_lshlrev_b32_e32 v4, 16, v24
	v_and_b32_e32 v5, 0xffff0000, v24
	v_lshlrev_b32_e32 v2, 16, v25
	v_and_b32_e32 v3, 0xffff0000, v25
	global_store_dwordx4 v[20:21], v[22:25], off offset:256 nt
	s_cbranch_vccnz .LBB0_696
	ds_read_b128 v[20:23], v239 offset:1536
	ds_read_b128 v[24:27], v239 offset:1552
	s_waitcnt lgkmcnt(1)
	v_pk_mul_f32 v[22:23], v[6:7], v[22:23]
	v_pk_mul_f32 v[20:21], v[8:9], v[20:21]
	s_waitcnt lgkmcnt(0)
	v_pk_mul_f32 v[26:27], v[2:3], v[26:27]
	v_pk_mul_f32 v[24:25], v[4:5], v[24:25]
	v_cvt_pk_bf16_f32 v20, v20, v21
	v_cvt_pk_bf16_f32 v21, v22, v23
	s_nop 0
	v_cvt_pk_bf16_f32 v22, v24, v25
	v_cvt_pk_bf16_f32 v23, v26, v27
	global_store_dwordx4 v[18:19], v[20:23], off offset:256 nt
